# previous stack + unit boundary: leading half's alignment barrier moved behind its epilogue loads (row scales / gate bytes in flight while it waits) in the w_in, branch and ff1 GEMMs
# speedup vs baseline: 1.0046x; 1.0046x over previous
.LBB0_297:
	s_add_u32 s0, s36, 0xfff80080
	s_addc_u32 s6, s37, -1
	s_add_i32 s49, 0, 0x10000
	s_cmp_eq_u32 s55, 28
	s_cselect_b32 s35, s25, s6
	s_cselect_b32 s34, s33, s0
	v_add_u32_e32 v156, s49, v159
	s_cselect_b32 s31, s40, s39
	s_cselect_b32 s30, s50, s38
	s_add_i32 s0, 0, 0x14000
	ds_read_b128 v[144:147], v156
	ds_read_b128 v[148:151], v156 offset:1024
	ds_read_b128 v[152:155], v156 offset:2048
	ds_read_b128 v[164:167], v156 offset:3072
	v_add_u32_e32 v156, s0, v159
	ds_read_b128 v[168:171], v156
	ds_read_b128 v[172:175], v156 offset:1024
	ds_read_b128 v[176:179], v156 offset:2048
	ds_read_b128 v[180:183], v156 offset:3072
	v_lshl_add_u64 v[156:157], s[36:37], 0, v[140:141]
	s_add_i32 m0, s47, 0xc000
	ds_read_b128 v[184:187], v163
	ds_read_b128 v[188:191], v163 offset:1024
	ds_read_b128 v[192:195], v163 offset:2048
	ds_read_b128 v[200:203], v163 offset:3072
	ds_read_b128 v[204:207], v163 offset:4096
	ds_read_b128 v[208:211], v163 offset:5120
	ds_read_b128 v[212:215], v163 offset:6144
	ds_read_b128 v[216:219], v163 offset:7168
	global_load_lds_dwordx4 v[156:157], off
	s_add_i32 m0, s47, 0xe000
	v_lshl_add_u64 v[156:157], s[36:37], 0, v[142:143]
	global_load_lds_dwordx4 v[156:157], off
	s_setprio 1
	s_waitcnt vmcnt(8) lgkmcnt(0)
	s_barrier
	v_mfma_f32_16x16x32_bf16 v[128:131], v[144:147], v[184:187], v[128:131]
	v_mfma_f32_16x16x32_bf16 v[124:127], v[152:155], v[184:187], v[124:127]
	v_mfma_f32_16x16x32_bf16 v[112:115], v[144:147], v[192:195], v[112:115]
	v_mfma_f32_16x16x32_bf16 v[108:111], v[152:155], v[192:195], v[108:111]
	v_mfma_f32_16x16x32_bf16 v[96:99], v[144:147], v[204:207], v[96:99]
	v_mfma_f32_16x16x32_bf16 v[92:95], v[152:155], v[204:207], v[92:95]
	v_mfma_f32_16x16x32_bf16 v[80:83], v[144:147], v[212:215], v[80:83]
	v_mfma_f32_16x16x32_bf16 v[76:79], v[152:155], v[212:215], v[76:79]
	v_mfma_f32_16x16x32_bf16 v[128:131], v[148:151], v[188:191], v[128:131]
	v_mfma_f32_16x16x32_bf16 v[124:127], v[164:167], v[188:191], v[124:127]
	v_mfma_f32_16x16x32_bf16 v[112:115], v[148:151], v[200:203], v[112:115]
	v_mfma_f32_16x16x32_bf16 v[108:111], v[164:167], v[200:203], v[108:111]
	v_mfma_f32_16x16x32_bf16 v[96:99], v[148:151], v[208:211], v[96:99]
	v_mfma_f32_16x16x32_bf16 v[92:95], v[164:167], v[208:211], v[92:95]
	v_mfma_f32_16x16x32_bf16 v[80:83], v[148:151], v[216:219], v[80:83]
	v_mfma_f32_16x16x32_bf16 v[76:79], v[164:167], v[216:219], v[76:79]
	s_setprio 0
	s_setprio 1
	v_mfma_f32_16x16x32_bf16 v[120:123], v[168:171], v[184:187], v[120:123]
	v_mfma_f32_16x16x32_bf16 v[116:119], v[176:179], v[184:187], v[116:119]
	v_mfma_f32_16x16x32_bf16 v[104:107], v[168:171], v[192:195], v[104:107]
	v_mfma_f32_16x16x32_bf16 v[100:103], v[176:179], v[192:195], v[100:103]
	v_mfma_f32_16x16x32_bf16 v[88:91], v[168:171], v[204:207], v[88:91]
	v_mfma_f32_16x16x32_bf16 v[84:87], v[176:179], v[204:207], v[84:87]
	v_mfma_f32_16x16x32_bf16 v[72:75], v[168:171], v[212:215], v[72:75]
	v_mfma_f32_16x16x32_bf16 v[68:71], v[176:179], v[212:215], v[68:71]
	v_mfma_f32_16x16x32_bf16 v[120:123], v[172:175], v[188:191], v[120:123]
	v_mfma_f32_16x16x32_bf16 v[116:119], v[180:183], v[188:191], v[116:119]
	v_mfma_f32_16x16x32_bf16 v[104:107], v[172:175], v[200:203], v[104:107]
	v_mfma_f32_16x16x32_bf16 v[100:103], v[180:183], v[200:203], v[100:103]
	v_mfma_f32_16x16x32_bf16 v[88:91], v[172:175], v[208:211], v[88:91]
	v_mfma_f32_16x16x32_bf16 v[84:87], v[180:183], v[208:211], v[84:87]
	v_mfma_f32_16x16x32_bf16 v[72:75], v[172:175], v[216:219], v[72:75]
	v_mfma_f32_16x16x32_bf16 v[68:71], v[180:183], v[216:219], v[68:71]
	s_barrier
	s_setprio 0
	s_add_i32 s6, s49, s46
	v_lshl_add_u64 v[156:157], s[30:31], 0, v[136:137]
	s_mov_b32 m0, s6
	ds_read_b128 v[184:187], v163 offset:16384
	ds_read_b128 v[188:191], v163 offset:17408
	ds_read_b128 v[192:195], v163 offset:18432
	ds_read_b128 v[200:203], v163 offset:19456
	ds_read_b128 v[204:207], v163 offset:20480
	ds_read_b128 v[208:211], v163 offset:21504
	ds_read_b128 v[212:215], v163 offset:22528
	ds_read_b128 v[216:219], v163 offset:23552
	global_load_lds_dwordx4 v[156:157], off
	s_add_i32 m0, s6, 0x2000
	s_add_u32 s66, s30, 0x80000
	v_lshl_add_u64 v[220:221], s[30:31], 0, v[132:133]
	s_addc_u32 s67, s31, 0
	s_add_i32 s0, s0, s46
	global_load_lds_dwordx4 v[220:221], off
	v_lshl_add_u64 v[222:223], s[66:67], 0, v[136:137]
	s_mov_b32 m0, s0
	global_load_lds_dwordx4 v[222:223], off
	s_add_i32 m0, s0, 0x2000
	v_lshl_add_u64 v[222:223], s[66:67], 0, v[132:133]
	global_load_lds_dwordx4 v[222:223], off
	s_mov_b32 m0, s47
	v_lshl_add_u64 v[222:223], s[34:35], 0, v[138:139]
	global_load_lds_dwordx4 v[222:223], off
	s_mov_b32 m0, s52
	v_lshl_add_u64 v[224:225], s[34:35], 0, v[134:135]
	global_load_lds_dwordx4 v[224:225], off
	s_setprio 1
	s_waitcnt vmcnt(8) lgkmcnt(0)
	s_barrier
	v_mfma_f32_16x16x32_bf16 v[64:67], v[144:147], v[184:187], v[64:67]
	v_mfma_f32_16x16x32_bf16 v[60:63], v[152:155], v[184:187], v[60:63]
	v_mfma_f32_16x16x32_bf16 v[48:51], v[144:147], v[192:195], v[48:51]
	v_mfma_f32_16x16x32_bf16 v[44:47], v[152:155], v[192:195], v[44:47]
	v_mfma_f32_16x16x32_bf16 v[32:35], v[144:147], v[204:207], v[32:35]
	v_mfma_f32_16x16x32_bf16 v[28:31], v[152:155], v[204:207], v[28:31]
	v_mfma_f32_16x16x32_bf16 v[16:19], v[144:147], v[212:215], v[16:19]
	v_mfma_f32_16x16x32_bf16 v[12:15], v[152:155], v[212:215], v[12:15]
	v_mfma_f32_16x16x32_bf16 v[64:67], v[148:151], v[188:191], v[64:67]
	v_mfma_f32_16x16x32_bf16 v[60:63], v[164:167], v[188:191], v[60:63]
	v_mfma_f32_16x16x32_bf16 v[48:51], v[148:151], v[200:203], v[48:51]
	v_mfma_f32_16x16x32_bf16 v[44:47], v[164:167], v[200:203], v[44:47]
	v_mfma_f32_16x16x32_bf16 v[32:35], v[148:151], v[208:211], v[32:35]
	v_mfma_f32_16x16x32_bf16 v[28:31], v[164:167], v[208:211], v[28:31]
	v_mfma_f32_16x16x32_bf16 v[16:19], v[148:151], v[216:219], v[16:19]
	v_mfma_f32_16x16x32_bf16 v[12:15], v[164:167], v[216:219], v[12:15]
	s_setprio 0
	s_setprio 1
	v_mfma_f32_16x16x32_bf16 v[56:59], v[168:171], v[184:187], v[56:59]
	v_mfma_f32_16x16x32_bf16 v[52:55], v[176:179], v[184:187], v[52:55]
	v_mfma_f32_16x16x32_bf16 v[40:43], v[168:171], v[192:195], v[40:43]
	v_mfma_f32_16x16x32_bf16 v[36:39], v[176:179], v[192:195], v[36:39]
	v_mfma_f32_16x16x32_bf16 v[24:27], v[168:171], v[204:207], v[24:27]
	v_mfma_f32_16x16x32_bf16 v[20:23], v[176:179], v[204:207], v[20:23]
	v_mfma_f32_16x16x32_bf16 v[8:11], v[168:171], v[212:215], v[8:11]
	v_mfma_f32_16x16x32_bf16 v[4:7], v[176:179], v[212:215], v[4:7]
	v_mfma_f32_16x16x32_bf16 v[56:59], v[172:175], v[188:191], v[56:59]
	v_mfma_f32_16x16x32_bf16 v[52:55], v[180:183], v[188:191], v[52:55]
	v_mfma_f32_16x16x32_bf16 v[40:43], v[172:175], v[200:203], v[40:43]
	v_mfma_f32_16x16x32_bf16 v[36:39], v[180:183], v[200:203], v[36:39]
	v_mfma_f32_16x16x32_bf16 v[24:27], v[172:175], v[208:211], v[24:27]
	v_mfma_f32_16x16x32_bf16 v[20:23], v[180:183], v[208:211], v[20:23]
	v_mfma_f32_16x16x32_bf16 v[8:11], v[172:175], v[216:219], v[8:11]
	v_mfma_f32_16x16x32_bf16 v[4:7], v[180:183], v[216:219], v[4:7]
	s_barrier
	s_setprio 0
	s_add_i32 s0, 0, 0x18000
	v_add_u32_e32 v158, s0, v159
	s_add_i32 s6, 0, 0x1c000
	ds_read_b128 v[144:147], v158
	ds_read_b128 v[148:151], v158 offset:1024
	ds_read_b128 v[152:155], v158 offset:2048
	ds_read_b128 v[164:167], v158 offset:3072
	v_add_u32_e32 v158, s6, v159
	ds_read_b128 v[168:171], v158
	ds_read_b128 v[172:175], v158 offset:1024
	ds_read_b128 v[176:179], v158 offset:2048
	ds_read_b128 v[180:183], v158 offset:3072
	s_add_u32 s34, s34, 0x80000
	s_addc_u32 s35, s35, 0
	s_mov_b32 m0, s53
	v_lshl_add_u64 v[226:227], s[34:35], 0, v[138:139]
	ds_read_b128 v[184:187], v163 offset:32768
	ds_read_b128 v[188:191], v163 offset:33792
	ds_read_b128 v[192:195], v163 offset:34816
	ds_read_b128 v[200:203], v163 offset:35840
	ds_read_b128 v[204:207], v163 offset:36864
	ds_read_b128 v[208:211], v163 offset:37888
	ds_read_b128 v[212:215], v163 offset:38912
	ds_read_b128 v[216:219], v163 offset:39936
	global_load_lds_dwordx4 v[226:227], off
	s_mov_b32 m0, s60
	v_lshl_add_u64 v[226:227], s[34:35], 0, v[134:135]
	global_load_lds_dwordx4 v[226:227], off
	s_setprio 1
	s_waitcnt vmcnt(8) lgkmcnt(0)
	s_barrier
	v_mfma_f32_16x16x32_bf16 v[128:131], v[144:147], v[184:187], v[128:131]
	v_mfma_f32_16x16x32_bf16 v[124:127], v[152:155], v[184:187], v[124:127]
	v_mfma_f32_16x16x32_bf16 v[112:115], v[144:147], v[192:195], v[112:115]
	v_mfma_f32_16x16x32_bf16 v[108:111], v[152:155], v[192:195], v[108:111]
	v_mfma_f32_16x16x32_bf16 v[96:99], v[144:147], v[204:207], v[96:99]
	v_mfma_f32_16x16x32_bf16 v[92:95], v[152:155], v[204:207], v[92:95]
	v_mfma_f32_16x16x32_bf16 v[80:83], v[144:147], v[212:215], v[80:83]
	v_mfma_f32_16x16x32_bf16 v[76:79], v[152:155], v[212:215], v[76:79]
	v_mfma_f32_16x16x32_bf16 v[128:131], v[148:151], v[188:191], v[128:131]
	v_mfma_f32_16x16x32_bf16 v[124:127], v[164:167], v[188:191], v[124:127]
	v_mfma_f32_16x16x32_bf16 v[112:115], v[148:151], v[200:203], v[112:115]
	v_mfma_f32_16x16x32_bf16 v[108:111], v[164:167], v[200:203], v[108:111]
	v_mfma_f32_16x16x32_bf16 v[96:99], v[148:151], v[208:211], v[96:99]
	v_mfma_f32_16x16x32_bf16 v[92:95], v[164:167], v[208:211], v[92:95]
	v_mfma_f32_16x16x32_bf16 v[80:83], v[148:151], v[216:219], v[80:83]
	v_mfma_f32_16x16x32_bf16 v[76:79], v[164:167], v[216:219], v[76:79]
	s_setprio 0
	s_setprio 1
	v_mfma_f32_16x16x32_bf16 v[120:123], v[168:171], v[184:187], v[120:123]
	v_mfma_f32_16x16x32_bf16 v[116:119], v[176:179], v[184:187], v[116:119]
	v_mfma_f32_16x16x32_bf16 v[104:107], v[168:171], v[192:195], v[104:107]
	v_mfma_f32_16x16x32_bf16 v[100:103], v[176:179], v[192:195], v[100:103]
	v_mfma_f32_16x16x32_bf16 v[88:91], v[168:171], v[204:207], v[88:91]
	v_mfma_f32_16x16x32_bf16 v[84:87], v[176:179], v[204:207], v[84:87]
	v_mfma_f32_16x16x32_bf16 v[72:75], v[168:171], v[212:215], v[72:75]
	v_mfma_f32_16x16x32_bf16 v[68:71], v[176:179], v[212:215], v[68:71]
	v_mfma_f32_16x16x32_bf16 v[120:123], v[172:175], v[188:191], v[120:123]
	v_mfma_f32_16x16x32_bf16 v[116:119], v[180:183], v[188:191], v[116:119]
	v_mfma_f32_16x16x32_bf16 v[104:107], v[172:175], v[200:203], v[104:107]
	v_mfma_f32_16x16x32_bf16 v[100:103], v[180:183], v[200:203], v[100:103]
	v_mfma_f32_16x16x32_bf16 v[88:91], v[172:175], v[208:211], v[88:91]
	v_mfma_f32_16x16x32_bf16 v[84:87], v[180:183], v[208:211], v[84:87]
	v_mfma_f32_16x16x32_bf16 v[72:75], v[172:175], v[216:219], v[72:75]
	v_mfma_f32_16x16x32_bf16 v[68:71], v[180:183], v[216:219], v[68:71]
	s_barrier
	s_setprio 0
	s_add_i32 s0, s0, s46
	v_lshl_add_u64 v[156:157], v[156:157], 0, s[90:91]
	s_mov_b32 m0, s0
	ds_read_b128 v[184:187], v163 offset:49152
	ds_read_b128 v[188:191], v163 offset:50176
	ds_read_b128 v[192:195], v163 offset:51200
	ds_read_b128 v[200:203], v163 offset:52224
	ds_read_b128 v[204:207], v163 offset:53248
	ds_read_b128 v[208:211], v163 offset:54272
	ds_read_b128 v[212:215], v163 offset:55296
	ds_read_b128 v[216:219], v163 offset:56320
	global_load_lds_dwordx4 v[156:157], off
	s_add_i32 m0, s0, 0x2000
	s_add_u32 s30, s30, 0x80080
	v_lshl_add_u64 v[156:157], v[220:221], 0, s[90:91]
	s_addc_u32 s31, s31, 0
	s_add_i32 s0, s6, s46
	global_load_lds_dwordx4 v[156:157], off
	s_mov_b32 m0, s0
	v_lshl_add_u64 v[156:157], s[30:31], 0, v[136:137]
	global_load_lds_dwordx4 v[156:157], off
	s_add_i32 m0, s0, 0x2000
	v_lshl_add_u64 v[156:157], s[30:31], 0, v[132:133]
	global_load_lds_dwordx4 v[156:157], off
	s_mov_b32 m0, s62
	v_lshl_add_u64 v[156:157], v[222:223], 0, s[90:91]
	global_load_lds_dwordx4 v[156:157], off
	s_mov_b32 m0, s51
	v_lshl_add_u64 v[156:157], v[224:225], 0, s[90:91]
	global_load_lds_dwordx4 v[156:157], off
	s_setprio 1
	s_waitcnt vmcnt(8) lgkmcnt(0)
	s_barrier
	v_mfma_f32_16x16x32_bf16 v[64:67], v[144:147], v[184:187], v[64:67]
	v_mfma_f32_16x16x32_bf16 v[60:63], v[152:155], v[184:187], v[60:63]
	v_mfma_f32_16x16x32_bf16 v[48:51], v[144:147], v[192:195], v[48:51]
	v_mfma_f32_16x16x32_bf16 v[44:47], v[152:155], v[192:195], v[44:47]
	v_mfma_f32_16x16x32_bf16 v[32:35], v[144:147], v[204:207], v[32:35]
	v_mfma_f32_16x16x32_bf16 v[28:31], v[152:155], v[204:207], v[28:31]
	v_mfma_f32_16x16x32_bf16 v[16:19], v[144:147], v[212:215], v[16:19]
	v_mfma_f32_16x16x32_bf16 v[12:15], v[152:155], v[212:215], v[12:15]
	v_mfma_f32_16x16x32_bf16 v[64:67], v[148:151], v[188:191], v[64:67]
	v_mfma_f32_16x16x32_bf16 v[60:63], v[164:167], v[188:191], v[60:63]
	v_mfma_f32_16x16x32_bf16 v[48:51], v[148:151], v[200:203], v[48:51]
	v_mfma_f32_16x16x32_bf16 v[44:47], v[164:167], v[200:203], v[44:47]
	v_mfma_f32_16x16x32_bf16 v[32:35], v[148:151], v[208:211], v[32:35]
	v_mfma_f32_16x16x32_bf16 v[28:31], v[164:167], v[208:211], v[28:31]
	v_mfma_f32_16x16x32_bf16 v[16:19], v[148:151], v[216:219], v[16:19]
	v_mfma_f32_16x16x32_bf16 v[12:15], v[164:167], v[216:219], v[12:15]
	s_setprio 0
	s_setprio 1
	v_mfma_f32_16x16x32_bf16 v[56:59], v[168:171], v[184:187], v[56:59]
	v_mfma_f32_16x16x32_bf16 v[52:55], v[176:179], v[184:187], v[52:55]
	v_mfma_f32_16x16x32_bf16 v[40:43], v[168:171], v[192:195], v[40:43]
	v_mfma_f32_16x16x32_bf16 v[36:39], v[176:179], v[192:195], v[36:39]
	v_mfma_f32_16x16x32_bf16 v[24:27], v[168:171], v[204:207], v[24:27]
	v_mfma_f32_16x16x32_bf16 v[20:23], v[176:179], v[204:207], v[20:23]
	v_mfma_f32_16x16x32_bf16 v[8:11], v[168:171], v[212:215], v[8:11]
	v_mfma_f32_16x16x32_bf16 v[4:7], v[176:179], v[212:215], v[4:7]
	v_mfma_f32_16x16x32_bf16 v[56:59], v[172:175], v[188:191], v[56:59]
	v_mfma_f32_16x16x32_bf16 v[52:55], v[180:183], v[188:191], v[52:55]
	v_mfma_f32_16x16x32_bf16 v[40:43], v[172:175], v[200:203], v[40:43]
	v_mfma_f32_16x16x32_bf16 v[36:39], v[180:183], v[200:203], v[36:39]
	v_mfma_f32_16x16x32_bf16 v[24:27], v[172:175], v[208:211], v[24:27]
	v_mfma_f32_16x16x32_bf16 v[20:23], v[180:183], v[208:211], v[20:23]
	v_mfma_f32_16x16x32_bf16 v[8:11], v[172:175], v[216:219], v[8:11]
	v_mfma_f32_16x16x32_bf16 v[4:7], v[180:183], v[216:219], v[4:7]
	s_barrier
	s_setprio 0
	s_add_i32 s55, s55, 2
	s_add_u32 s36, s36, 0x100
	s_addc_u32 s37, s37, 0
	s_add_u32 s38, s38, 0x100
	s_addc_u32 s39, s39, 0
	s_cmp_gt_u32 s55, 29
	s_cbranch_scc0 .LBB0_297
	s_and_b64 vcc, exec, s[22:23]
	s_mov_b32 s100, 0
	s_cbranch_vccz .LBB0_300
	s_mov_b32 s100, 1
.LBB0_300:
	v_lshl_add_u32 v156, s24, 8, v3
	v_ashrrev_i32_e32 v157, 31, v156
	v_lshl_add_u64 v[164:165], v[156:157], 3, s[18:19]
	global_load_dwordx2 v[168:169], v[164:165], off
	v_or_b32_e32 v148, 16, v156
	v_ashrrev_i32_e32 v149, 31, v148
	v_lshl_add_u64 v[144:145], v[148:149], 3, s[18:19]
	global_load_dwordx2 v[170:171], v[144:145], off
	v_or_b32_e32 v146, 32, v156
	v_ashrrev_i32_e32 v147, 31, v146
	v_lshl_add_u64 v[144:145], v[146:147], 3, s[18:19]
	global_load_dwordx2 v[172:173], v[144:145], off
	global_load_dwordx2 v[152:153], v[164:165], off offset:1152
	v_or_b32_e32 v144, 48, v156
	v_ashrrev_i32_e32 v145, 31, v144
	v_lshl_add_u64 v[150:151], v[144:145], 3, s[18:19]
	global_load_dwordx2 v[154:155], v[150:151], off
	global_load_dwordx2 v[166:167], v[164:165], off offset:1280
	v_mov_b32_e32 v175, v2
	global_load_dwordx2 v[150:151], v[164:165], off offset:1024
	s_min_u32 s24, s72, 32
	global_load_dwordx2 v[164:165], v[164:165], off offset:1408
	s_sub_i32 s25, 32, s24
	v_add_u32_e32 v157, 0x80, v156
	v_add_u32_e32 v149, 0x90, v156
	v_add_u32_e32 v147, 0xa0, v156
	v_add_u32_e32 v145, 0xb0, v156
	s_mov_b64 s[30:31], -1
	s_cmp_eq_u32 s100, 0
	s_cbranch_scc1 .Lx_ab_0
	s_barrier
.Lx_ab_0:
	s_cmp_gt_i32 s1, 7
	s_waitcnt vmcnt(0)
	v_mov_b32_e32 v174, v169
	v_lshlrev_b64 v[174:175], s24, v[174:175]
	v_min_u32_e32 v158, 1, v174
	v_or_b32_e32 v158, v175, v158
	v_cvt_f32_u32_e32 v158, v158
	v_cvt_f32_u32_e32 v160, v168
	v_mov_b32_e32 v168, v171
	v_mov_b32_e32 v169, v2
	v_ldexp_f32 v158, v158, s25
	v_mul_f32_e32 v158, 0x43800000, v158
	v_fmac_f32_e32 v158, 0x33800000, v160
	v_fmamk_f32 v158, v158, 0x3a000000, v1
	v_lshlrev_b64 v[168:169], s24, v[168:169]
	v_rsq_f32_e32 v162, v158
	v_min_u32_e32 v158, 1, v168
	v_or_b32_e32 v158, v169, v158
	v_cvt_f32_u32_e32 v158, v158
	v_cvt_f32_u32_e32 v160, v170
	v_mov_b32_e32 v168, v173
	v_mov_b32_e32 v169, v2
	v_ldexp_f32 v158, v158, s25
	v_mul_f32_e32 v158, 0x43800000, v158
	v_fmac_f32_e32 v158, 0x33800000, v160
	v_fmamk_f32 v158, v158, 0x3a000000, v1
	v_lshlrev_b64 v[168:169], s24, v[168:169]
	v_rsq_f32_e32 v160, v158
	v_min_u32_e32 v158, 1, v168
	v_or_b32_e32 v158, v169, v158
	v_cvt_f32_u32_e32 v158, v158
	v_cvt_f32_u32_e32 v168, v172
	v_mov_b32_e32 v169, v2
	v_cvt_f32_u32_e32 v150, v150
	v_ldexp_f32 v158, v158, s25
	v_mul_f32_e32 v158, 0x43800000, v158
	v_fmac_f32_e32 v158, 0x33800000, v168
	v_mov_b32_e32 v168, v155
	v_lshlrev_b64 v[168:169], s24, v[168:169]
	v_min_u32_e32 v155, 1, v168
	v_or_b32_e32 v155, v169, v155
	v_mov_b32_e32 v168, v151
	v_mov_b32_e32 v169, v2
	v_lshlrev_b64 v[168:169], s24, v[168:169]
	v_min_u32_e32 v151, 1, v168
	v_or_b32_e32 v151, v169, v151
	v_cvt_f32_u32_e32 v151, v151
	v_mov_b32_e32 v168, v153
	v_mov_b32_e32 v169, v2
	v_lshlrev_b64 v[168:169], s24, v[168:169]
	v_ldexp_f32 v151, v151, s25
	v_mul_f32_e32 v151, 0x43800000, v151
	v_fmac_f32_e32 v151, 0x33800000, v150
	v_fmamk_f32 v150, v151, 0x3a000000, v1
	v_min_u32_e32 v151, 1, v168
	v_or_b32_e32 v151, v169, v151
	v_cvt_f32_u32_e32 v151, v151
	v_cvt_f32_u32_e32 v152, v152
	v_mov_b32_e32 v168, v167
	v_mov_b32_e32 v169, v2
	v_ldexp_f32 v151, v151, s25
	v_mul_f32_e32 v151, 0x43800000, v151
	v_fmac_f32_e32 v151, 0x33800000, v152
	v_fmamk_f32 v151, v151, 0x3a000000, v1
	v_lshlrev_b64 v[168:169], s24, v[168:169]
	v_rsq_f32_e32 v152, v151
	v_min_u32_e32 v151, 1, v168
	v_or_b32_e32 v151, v169, v151
	v_cvt_f32_u32_e32 v151, v151
	v_cvt_f32_u32_e32 v153, v166
	v_mov_b32_e32 v168, v165
	v_mov_b32_e32 v169, v2
	v_ldexp_f32 v151, v151, s25
	v_mul_f32_e32 v151, 0x43800000, v151
	v_fmac_f32_e32 v151, 0x33800000, v153
	v_fmamk_f32 v151, v151, 0x3a000000, v1
	v_lshlrev_b64 v[168:169], s24, v[168:169]
	v_rsq_f32_e32 v166, v151
	v_min_u32_e32 v151, 1, v168
	v_or_b32_e32 v151, v169, v151
	v_cvt_f32_u32_e32 v155, v155
	v_cvt_f32_u32_e32 v151, v151
	v_cvt_f32_u32_e32 v154, v154
	v_cvt_f32_u32_e32 v153, v164
	v_ldexp_f32 v155, v155, s25
	v_ldexp_f32 v151, v151, s25
	v_mul_f32_e32 v155, 0x43800000, v155
	v_mul_f32_e32 v151, 0x43800000, v151
	v_fmac_f32_e32 v155, 0x33800000, v154
	v_fmac_f32_e32 v151, 0x33800000, v153
	v_fmamk_f32 v158, v158, 0x3a000000, v1
	v_fmamk_f32 v154, v155, 0x3a000000, v1
	v_fmamk_f32 v151, v151, 0x3a000000, v1
	v_rsq_f32_e32 v158, v158
	v_rsq_f32_e32 v154, v154
	v_rsq_f32_e32 v150, v150
	v_rsq_f32_e32 v164, v151
	v_lshl_or_b32 v168, s1, 8, v161
	s_cbranch_scc1 .LBB0_303
	s_andn2_b64 vcc, exec, s[30:31]
	s_cbranch_vccz .LBB0_308

.LBB0_336:
	s_add_u32 s0, s36, 0xfff80080
	s_addc_u32 s6, s37, -1
	s_add_i32 s49, 0, 0x10000
	s_cmp_eq_u32 s50, 28
	s_cselect_b32 s35, s24, s6
	s_cselect_b32 s34, s25, s0
	v_add_u32_e32 v156, s49, v159
	s_cselect_b32 s31, s33, s39
	s_cselect_b32 s30, s40, s38
	s_add_i32 s0, 0, 0x14000
	ds_read_b128 v[144:147], v156
	ds_read_b128 v[148:151], v156 offset:1024
	ds_read_b128 v[152:155], v156 offset:2048
	ds_read_b128 v[164:167], v156 offset:3072
	v_add_u32_e32 v156, s0, v159
	ds_read_b128 v[168:171], v156
	ds_read_b128 v[172:175], v156 offset:1024
	ds_read_b128 v[176:179], v156 offset:2048
	ds_read_b128 v[180:183], v156 offset:3072
	v_lshl_add_u64 v[156:157], s[36:37], 0, v[140:141]
	s_add_i32 m0, s45, 0xc000
	ds_read_b128 v[184:187], v163
	ds_read_b128 v[188:191], v163 offset:1024
	ds_read_b128 v[192:195], v163 offset:2048
	ds_read_b128 v[200:203], v163 offset:3072
	ds_read_b128 v[204:207], v163 offset:4096
	ds_read_b128 v[208:211], v163 offset:5120
	ds_read_b128 v[212:215], v163 offset:6144
	ds_read_b128 v[216:219], v163 offset:7168
	global_load_lds_dwordx4 v[156:157], off
	s_add_i32 m0, s45, 0xe000
	v_lshl_add_u64 v[156:157], s[36:37], 0, v[142:143]
	global_load_lds_dwordx4 v[156:157], off
	s_setprio 1
	s_waitcnt vmcnt(8) lgkmcnt(0)
	s_barrier
	v_mfma_f32_16x16x32_bf16 v[128:131], v[144:147], v[184:187], v[128:131]
	v_mfma_f32_16x16x32_bf16 v[124:127], v[152:155], v[184:187], v[124:127]
	v_mfma_f32_16x16x32_bf16 v[112:115], v[144:147], v[192:195], v[112:115]
	v_mfma_f32_16x16x32_bf16 v[108:111], v[152:155], v[192:195], v[108:111]
	v_mfma_f32_16x16x32_bf16 v[96:99], v[144:147], v[204:207], v[96:99]
	v_mfma_f32_16x16x32_bf16 v[92:95], v[152:155], v[204:207], v[92:95]
	v_mfma_f32_16x16x32_bf16 v[80:83], v[144:147], v[212:215], v[80:83]
	v_mfma_f32_16x16x32_bf16 v[76:79], v[152:155], v[212:215], v[76:79]
	v_mfma_f32_16x16x32_bf16 v[128:131], v[148:151], v[188:191], v[128:131]
	v_mfma_f32_16x16x32_bf16 v[124:127], v[164:167], v[188:191], v[124:127]
	v_mfma_f32_16x16x32_bf16 v[112:115], v[148:151], v[200:203], v[112:115]
	v_mfma_f32_16x16x32_bf16 v[108:111], v[164:167], v[200:203], v[108:111]
	v_mfma_f32_16x16x32_bf16 v[96:99], v[148:151], v[208:211], v[96:99]
	v_mfma_f32_16x16x32_bf16 v[92:95], v[164:167], v[208:211], v[92:95]
	v_mfma_f32_16x16x32_bf16 v[80:83], v[148:151], v[216:219], v[80:83]
	v_mfma_f32_16x16x32_bf16 v[76:79], v[164:167], v[216:219], v[76:79]
	s_setprio 0
	s_setprio 1
	v_mfma_f32_16x16x32_bf16 v[120:123], v[168:171], v[184:187], v[120:123]
	v_mfma_f32_16x16x32_bf16 v[116:119], v[176:179], v[184:187], v[116:119]
	v_mfma_f32_16x16x32_bf16 v[104:107], v[168:171], v[192:195], v[104:107]
	v_mfma_f32_16x16x32_bf16 v[100:103], v[176:179], v[192:195], v[100:103]
	v_mfma_f32_16x16x32_bf16 v[88:91], v[168:171], v[204:207], v[88:91]
	v_mfma_f32_16x16x32_bf16 v[84:87], v[176:179], v[204:207], v[84:87]
	v_mfma_f32_16x16x32_bf16 v[72:75], v[168:171], v[212:215], v[72:75]
	v_mfma_f32_16x16x32_bf16 v[68:71], v[176:179], v[212:215], v[68:71]
	v_mfma_f32_16x16x32_bf16 v[120:123], v[172:175], v[188:191], v[120:123]
	v_mfma_f32_16x16x32_bf16 v[116:119], v[180:183], v[188:191], v[116:119]
	v_mfma_f32_16x16x32_bf16 v[104:107], v[172:175], v[200:203], v[104:107]
	v_mfma_f32_16x16x32_bf16 v[100:103], v[180:183], v[200:203], v[100:103]
	v_mfma_f32_16x16x32_bf16 v[88:91], v[172:175], v[208:211], v[88:91]
	v_mfma_f32_16x16x32_bf16 v[84:87], v[180:183], v[208:211], v[84:87]
	v_mfma_f32_16x16x32_bf16 v[72:75], v[172:175], v[216:219], v[72:75]
	v_mfma_f32_16x16x32_bf16 v[68:71], v[180:183], v[216:219], v[68:71]
	s_barrier
	s_setprio 0
	s_add_i32 s6, s49, s47
	v_lshl_add_u64 v[156:157], s[30:31], 0, v[136:137]
	s_mov_b32 m0, s6
	ds_read_b128 v[184:187], v163 offset:16384
	ds_read_b128 v[188:191], v163 offset:17408
	ds_read_b128 v[192:195], v163 offset:18432
	ds_read_b128 v[200:203], v163 offset:19456
	ds_read_b128 v[204:207], v163 offset:20480
	ds_read_b128 v[208:211], v163 offset:21504
	ds_read_b128 v[212:215], v163 offset:22528
	ds_read_b128 v[216:219], v163 offset:23552
	global_load_lds_dwordx4 v[156:157], off
	s_add_i32 m0, s6, 0x2000
	s_add_u32 s54, s30, 0x80000
	v_lshl_add_u64 v[220:221], s[30:31], 0, v[132:133]
	s_addc_u32 s55, s31, 0
	s_add_i32 s0, s0, s47
	global_load_lds_dwordx4 v[220:221], off
	v_lshl_add_u64 v[222:223], s[54:55], 0, v[136:137]
	s_mov_b32 m0, s0
	global_load_lds_dwordx4 v[222:223], off
	s_add_i32 m0, s0, 0x2000
	v_lshl_add_u64 v[222:223], s[54:55], 0, v[132:133]
	global_load_lds_dwordx4 v[222:223], off
	s_mov_b32 m0, s45
	v_lshl_add_u64 v[222:223], s[34:35], 0, v[138:139]
	global_load_lds_dwordx4 v[222:223], off
	s_mov_b32 m0, s61
	v_lshl_add_u64 v[224:225], s[34:35], 0, v[134:135]
	global_load_lds_dwordx4 v[224:225], off
	s_setprio 1
	s_waitcnt vmcnt(8) lgkmcnt(0)
	s_barrier
	v_mfma_f32_16x16x32_bf16 v[64:67], v[144:147], v[184:187], v[64:67]
	v_mfma_f32_16x16x32_bf16 v[60:63], v[152:155], v[184:187], v[60:63]
	v_mfma_f32_16x16x32_bf16 v[48:51], v[144:147], v[192:195], v[48:51]
	v_mfma_f32_16x16x32_bf16 v[44:47], v[152:155], v[192:195], v[44:47]
	v_mfma_f32_16x16x32_bf16 v[32:35], v[144:147], v[204:207], v[32:35]
	v_mfma_f32_16x16x32_bf16 v[28:31], v[152:155], v[204:207], v[28:31]
	v_mfma_f32_16x16x32_bf16 v[16:19], v[144:147], v[212:215], v[16:19]
	v_mfma_f32_16x16x32_bf16 v[12:15], v[152:155], v[212:215], v[12:15]
	v_mfma_f32_16x16x32_bf16 v[64:67], v[148:151], v[188:191], v[64:67]
	v_mfma_f32_16x16x32_bf16 v[60:63], v[164:167], v[188:191], v[60:63]
	v_mfma_f32_16x16x32_bf16 v[48:51], v[148:151], v[200:203], v[48:51]
	v_mfma_f32_16x16x32_bf16 v[44:47], v[164:167], v[200:203], v[44:47]
	v_mfma_f32_16x16x32_bf16 v[32:35], v[148:151], v[208:211], v[32:35]
	v_mfma_f32_16x16x32_bf16 v[28:31], v[164:167], v[208:211], v[28:31]
	v_mfma_f32_16x16x32_bf16 v[16:19], v[148:151], v[216:219], v[16:19]
	v_mfma_f32_16x16x32_bf16 v[12:15], v[164:167], v[216:219], v[12:15]
	s_setprio 0
	s_setprio 1
	v_mfma_f32_16x16x32_bf16 v[56:59], v[168:171], v[184:187], v[56:59]
	v_mfma_f32_16x16x32_bf16 v[52:55], v[176:179], v[184:187], v[52:55]
	v_mfma_f32_16x16x32_bf16 v[40:43], v[168:171], v[192:195], v[40:43]
	v_mfma_f32_16x16x32_bf16 v[36:39], v[176:179], v[192:195], v[36:39]
	v_mfma_f32_16x16x32_bf16 v[24:27], v[168:171], v[204:207], v[24:27]
	v_mfma_f32_16x16x32_bf16 v[20:23], v[176:179], v[204:207], v[20:23]
	v_mfma_f32_16x16x32_bf16 v[8:11], v[168:171], v[212:215], v[8:11]
	v_mfma_f32_16x16x32_bf16 v[4:7], v[176:179], v[212:215], v[4:7]
	v_mfma_f32_16x16x32_bf16 v[56:59], v[172:175], v[188:191], v[56:59]
	v_mfma_f32_16x16x32_bf16 v[52:55], v[180:183], v[188:191], v[52:55]
	v_mfma_f32_16x16x32_bf16 v[40:43], v[172:175], v[200:203], v[40:43]
	v_mfma_f32_16x16x32_bf16 v[36:39], v[180:183], v[200:203], v[36:39]
	v_mfma_f32_16x16x32_bf16 v[24:27], v[172:175], v[208:211], v[24:27]
	v_mfma_f32_16x16x32_bf16 v[20:23], v[180:183], v[208:211], v[20:23]
	v_mfma_f32_16x16x32_bf16 v[8:11], v[172:175], v[216:219], v[8:11]
	v_mfma_f32_16x16x32_bf16 v[4:7], v[180:183], v[216:219], v[4:7]
	s_barrier
	s_setprio 0
	s_add_i32 s0, 0, 0x18000
	v_add_u32_e32 v158, s0, v159
	s_add_i32 s6, 0, 0x1c000
	ds_read_b128 v[144:147], v158
	ds_read_b128 v[148:151], v158 offset:1024
	ds_read_b128 v[152:155], v158 offset:2048
	ds_read_b128 v[164:167], v158 offset:3072
	v_add_u32_e32 v158, s6, v159
	ds_read_b128 v[168:171], v158
	ds_read_b128 v[172:175], v158 offset:1024
	ds_read_b128 v[176:179], v158 offset:2048
	ds_read_b128 v[180:183], v158 offset:3072
	s_add_u32 s34, s34, 0x80000
	s_addc_u32 s35, s35, 0
	s_mov_b32 m0, s62
	v_lshl_add_u64 v[226:227], s[34:35], 0, v[138:139]
	ds_read_b128 v[184:187], v163 offset:32768
	ds_read_b128 v[188:191], v163 offset:33792
	ds_read_b128 v[192:195], v163 offset:34816
	ds_read_b128 v[200:203], v163 offset:35840
	ds_read_b128 v[204:207], v163 offset:36864
	ds_read_b128 v[208:211], v163 offset:37888
	ds_read_b128 v[212:215], v163 offset:38912
	ds_read_b128 v[216:219], v163 offset:39936
	global_load_lds_dwordx4 v[226:227], off
	s_mov_b32 m0, s63
	v_lshl_add_u64 v[226:227], s[34:35], 0, v[134:135]
	global_load_lds_dwordx4 v[226:227], off
	s_setprio 1
	s_waitcnt vmcnt(8) lgkmcnt(0)
	s_barrier
	v_mfma_f32_16x16x32_bf16 v[128:131], v[144:147], v[184:187], v[128:131]
	v_mfma_f32_16x16x32_bf16 v[124:127], v[152:155], v[184:187], v[124:127]
	v_mfma_f32_16x16x32_bf16 v[112:115], v[144:147], v[192:195], v[112:115]
	v_mfma_f32_16x16x32_bf16 v[108:111], v[152:155], v[192:195], v[108:111]
	v_mfma_f32_16x16x32_bf16 v[96:99], v[144:147], v[204:207], v[96:99]
	v_mfma_f32_16x16x32_bf16 v[92:95], v[152:155], v[204:207], v[92:95]
	v_mfma_f32_16x16x32_bf16 v[80:83], v[144:147], v[212:215], v[80:83]
	v_mfma_f32_16x16x32_bf16 v[76:79], v[152:155], v[212:215], v[76:79]
	v_mfma_f32_16x16x32_bf16 v[128:131], v[148:151], v[188:191], v[128:131]
	v_mfma_f32_16x16x32_bf16 v[124:127], v[164:167], v[188:191], v[124:127]
	v_mfma_f32_16x16x32_bf16 v[112:115], v[148:151], v[200:203], v[112:115]
	v_mfma_f32_16x16x32_bf16 v[108:111], v[164:167], v[200:203], v[108:111]
	v_mfma_f32_16x16x32_bf16 v[96:99], v[148:151], v[208:211], v[96:99]
	v_mfma_f32_16x16x32_bf16 v[92:95], v[164:167], v[208:211], v[92:95]
	v_mfma_f32_16x16x32_bf16 v[80:83], v[148:151], v[216:219], v[80:83]
	v_mfma_f32_16x16x32_bf16 v[76:79], v[164:167], v[216:219], v[76:79]
	s_setprio 0
	s_setprio 1
	v_mfma_f32_16x16x32_bf16 v[120:123], v[168:171], v[184:187], v[120:123]
	v_mfma_f32_16x16x32_bf16 v[116:119], v[176:179], v[184:187], v[116:119]
	v_mfma_f32_16x16x32_bf16 v[104:107], v[168:171], v[192:195], v[104:107]
	v_mfma_f32_16x16x32_bf16 v[100:103], v[176:179], v[192:195], v[100:103]
	v_mfma_f32_16x16x32_bf16 v[88:91], v[168:171], v[204:207], v[88:91]
	v_mfma_f32_16x16x32_bf16 v[84:87], v[176:179], v[204:207], v[84:87]
	v_mfma_f32_16x16x32_bf16 v[72:75], v[168:171], v[212:215], v[72:75]
	v_mfma_f32_16x16x32_bf16 v[68:71], v[176:179], v[212:215], v[68:71]
	v_mfma_f32_16x16x32_bf16 v[120:123], v[172:175], v[188:191], v[120:123]
	v_mfma_f32_16x16x32_bf16 v[116:119], v[180:183], v[188:191], v[116:119]
	v_mfma_f32_16x16x32_bf16 v[104:107], v[172:175], v[200:203], v[104:107]
	v_mfma_f32_16x16x32_bf16 v[100:103], v[180:183], v[200:203], v[100:103]
	v_mfma_f32_16x16x32_bf16 v[88:91], v[172:175], v[208:211], v[88:91]
	v_mfma_f32_16x16x32_bf16 v[84:87], v[180:183], v[208:211], v[84:87]
	v_mfma_f32_16x16x32_bf16 v[72:75], v[172:175], v[216:219], v[72:75]
	v_mfma_f32_16x16x32_bf16 v[68:71], v[180:183], v[216:219], v[68:71]
	s_barrier
	s_setprio 0
	s_add_i32 s0, s0, s47
	v_lshl_add_u64 v[156:157], v[156:157], 0, s[90:91]
	s_mov_b32 m0, s0
	ds_read_b128 v[184:187], v163 offset:49152
	ds_read_b128 v[188:191], v163 offset:50176
	ds_read_b128 v[192:195], v163 offset:51200
	ds_read_b128 v[200:203], v163 offset:52224
	ds_read_b128 v[204:207], v163 offset:53248
	ds_read_b128 v[208:211], v163 offset:54272
	ds_read_b128 v[212:215], v163 offset:55296
	ds_read_b128 v[216:219], v163 offset:56320
	global_load_lds_dwordx4 v[156:157], off
	s_add_i32 m0, s0, 0x2000
	s_add_u32 s30, s30, 0x80080
	v_lshl_add_u64 v[156:157], v[220:221], 0, s[90:91]
	s_addc_u32 s31, s31, 0
	s_add_i32 s0, s6, s47
	global_load_lds_dwordx4 v[156:157], off
	s_mov_b32 m0, s0
	v_lshl_add_u64 v[156:157], s[30:31], 0, v[136:137]
	global_load_lds_dwordx4 v[156:157], off
	s_add_i32 m0, s0, 0x2000
	v_lshl_add_u64 v[156:157], s[30:31], 0, v[132:133]
	global_load_lds_dwordx4 v[156:157], off
	s_mov_b32 m0, s51
	v_lshl_add_u64 v[156:157], v[222:223], 0, s[90:91]
	global_load_lds_dwordx4 v[156:157], off
	s_mov_b32 m0, s4
	v_lshl_add_u64 v[156:157], v[224:225], 0, s[90:91]
	global_load_lds_dwordx4 v[156:157], off
	s_setprio 1
	s_waitcnt vmcnt(8) lgkmcnt(0)
	s_barrier
	v_mfma_f32_16x16x32_bf16 v[64:67], v[144:147], v[184:187], v[64:67]
	v_mfma_f32_16x16x32_bf16 v[60:63], v[152:155], v[184:187], v[60:63]
	v_mfma_f32_16x16x32_bf16 v[48:51], v[144:147], v[192:195], v[48:51]
	v_mfma_f32_16x16x32_bf16 v[44:47], v[152:155], v[192:195], v[44:47]
	v_mfma_f32_16x16x32_bf16 v[32:35], v[144:147], v[204:207], v[32:35]
	v_mfma_f32_16x16x32_bf16 v[28:31], v[152:155], v[204:207], v[28:31]
	v_mfma_f32_16x16x32_bf16 v[16:19], v[144:147], v[212:215], v[16:19]
	v_mfma_f32_16x16x32_bf16 v[12:15], v[152:155], v[212:215], v[12:15]
	v_mfma_f32_16x16x32_bf16 v[64:67], v[148:151], v[188:191], v[64:67]
	v_mfma_f32_16x16x32_bf16 v[60:63], v[164:167], v[188:191], v[60:63]
	v_mfma_f32_16x16x32_bf16 v[48:51], v[148:151], v[200:203], v[48:51]
	v_mfma_f32_16x16x32_bf16 v[44:47], v[164:167], v[200:203], v[44:47]
	v_mfma_f32_16x16x32_bf16 v[32:35], v[148:151], v[208:211], v[32:35]
	v_mfma_f32_16x16x32_bf16 v[28:31], v[164:167], v[208:211], v[28:31]
	v_mfma_f32_16x16x32_bf16 v[16:19], v[148:151], v[216:219], v[16:19]
	v_mfma_f32_16x16x32_bf16 v[12:15], v[164:167], v[216:219], v[12:15]
	s_setprio 0
	s_setprio 1
	v_mfma_f32_16x16x32_bf16 v[56:59], v[168:171], v[184:187], v[56:59]
	v_mfma_f32_16x16x32_bf16 v[52:55], v[176:179], v[184:187], v[52:55]
	v_mfma_f32_16x16x32_bf16 v[40:43], v[168:171], v[192:195], v[40:43]
	v_mfma_f32_16x16x32_bf16 v[36:39], v[176:179], v[192:195], v[36:39]
	v_mfma_f32_16x16x32_bf16 v[24:27], v[168:171], v[204:207], v[24:27]
	v_mfma_f32_16x16x32_bf16 v[20:23], v[176:179], v[204:207], v[20:23]
	v_mfma_f32_16x16x32_bf16 v[8:11], v[168:171], v[212:215], v[8:11]
	v_mfma_f32_16x16x32_bf16 v[4:7], v[176:179], v[212:215], v[4:7]
	v_mfma_f32_16x16x32_bf16 v[56:59], v[172:175], v[188:191], v[56:59]
	v_mfma_f32_16x16x32_bf16 v[52:55], v[180:183], v[188:191], v[52:55]
	v_mfma_f32_16x16x32_bf16 v[40:43], v[172:175], v[200:203], v[40:43]
	v_mfma_f32_16x16x32_bf16 v[36:39], v[180:183], v[200:203], v[36:39]
	v_mfma_f32_16x16x32_bf16 v[24:27], v[172:175], v[208:211], v[24:27]
	v_mfma_f32_16x16x32_bf16 v[20:23], v[180:183], v[208:211], v[20:23]
	v_mfma_f32_16x16x32_bf16 v[8:11], v[172:175], v[216:219], v[8:11]
	v_mfma_f32_16x16x32_bf16 v[4:7], v[180:183], v[216:219], v[4:7]
	s_barrier
	s_setprio 0
	s_add_i32 s50, s50, 2
	s_add_u32 s36, s36, 0x100
	s_addc_u32 s37, s37, 0
	s_add_u32 s38, s38, 0x100
	s_addc_u32 s39, s39, 0
	s_cmp_gt_u32 s50, 29
	s_cbranch_scc0 .LBB0_336
	s_and_b64 vcc, exec, s[22:23]
	s_mov_b32 s100, 0
	s_cbranch_vccz .LBB0_339
	s_mov_b32 s100, 1
.LBB0_339:
	v_lshl_add_u32 v156, s44, 8, v3
	v_ashrrev_i32_e32 v157, 31, v156
	v_lshl_add_u64 v[164:165], v[156:157], 3, s[18:19]
	global_load_dwordx2 v[168:169], v[164:165], off
	v_or_b32_e32 v148, 16, v156
	v_ashrrev_i32_e32 v149, 31, v148
	v_lshl_add_u64 v[144:145], v[148:149], 3, s[18:19]
	global_load_dwordx2 v[170:171], v[144:145], off
	v_or_b32_e32 v146, 32, v156
	v_ashrrev_i32_e32 v147, 31, v146
	v_lshl_add_u64 v[144:145], v[146:147], 3, s[18:19]
	global_load_dwordx2 v[172:173], v[144:145], off
	global_load_dwordx2 v[152:153], v[164:165], off offset:1152
	v_or_b32_e32 v144, 48, v156
	v_ashrrev_i32_e32 v145, 31, v144
	v_lshl_add_u64 v[150:151], v[144:145], 3, s[18:19]
	global_load_dwordx2 v[154:155], v[150:151], off
	global_load_dwordx2 v[166:167], v[164:165], off offset:1280
	v_mov_b32_e32 v175, v2
	global_load_dwordx2 v[150:151], v[164:165], off offset:1024
	s_min_u32 s24, s72, 32
	global_load_dwordx2 v[164:165], v[164:165], off offset:1408
	s_sub_i32 s25, 32, s24
	v_add_u32_e32 v157, 0x80, v156
	v_add_u32_e32 v149, 0x90, v156
	v_add_u32_e32 v147, 0xa0, v156
	v_add_u32_e32 v145, 0xb0, v156
	s_mov_b64 s[30:31], -1
	s_cmp_eq_u32 s100, 0
	s_cbranch_scc1 .Lx_ab_1
	s_barrier

.LBB0_748:
	s_and_b64 vcc, exec, s[22:23]
	s_mov_b32 s100, 0
	s_cbranch_vccz .LBB0_750
	s_mov_b32 s100, 1

.LBB0_754:
	global_load_dwordx2 v[238:239], v[180:181], off
	global_load_dwordx2 v[226:227], v[180:181], off offset:128
	global_load_dwordx2 v[224:225], v[152:153], off
	global_load_dwordx2 v[218:219], v[152:153], off offset:128
	global_load_dwordx2 v[214:215], v[160:161], off
	global_load_dwordx2 v[208:209], v[160:161], off offset:128
	global_load_dwordx2 v[204:205], v[164:165], off
	global_load_dwordx2 v[194:195], v[164:165], off offset:128
	global_load_dwordx2 v[190:191], v[170:171], off
	global_load_dwordx2 v[184:185], v[170:171], off offset:128
	global_load_dwordx2 v[180:181], v[174:175], off
	s_nop 0
	global_load_dwordx2 v[174:175], v[174:175], off offset:128
	s_nop 0
	global_load_dwordx2 v[170:171], v[228:229], off
	global_load_dwordx2 v[164:165], v[228:229], off offset:128
	global_load_dwordx2 v[160:161], v[230:231], off
	global_load_dwordx2 v[152:153], v[230:231], off offset:128
	s_xor_b64 s[0:1], s[14:15], -1
	v_cndmask_b32_e64 v3, 0, 1, s[0:1]
	v_cmp_ne_u32_e64 s[12:13], 1, v3
	s_andn2_b64 vcc, exec, s[0:1]
	s_mov_b64 s[14:15], -1
	s_cmp_eq_u32 s100, 0
	s_cbranch_scc1 .Lx_ab_2
	s_barrier
.Lx_ab_2:
	s_waitcnt vmcnt(15)
	v_cvt_f32_ubyte1_e32 v233, v238
	v_cvt_f32_ubyte0_e32 v232, v238
	v_cvt_f32_ubyte3_e32 v235, v238
	v_cvt_f32_ubyte2_e32 v234, v238
	v_cvt_f32_ubyte1_e32 v229, v239
	v_cvt_f32_ubyte0_e32 v228, v239
	v_cvt_f32_ubyte3_e32 v231, v239
	v_cvt_f32_ubyte2_e32 v230, v239
	s_cbranch_vccnz .LBB0_760
	v_mul_f32_e32 v3, 0x3b808081, v232
	v_mul_f32_e32 v157, 0x3b808081, v233
	v_mul_f32_e32 v169, 0x3b808081, v234
	v_mul_f32_e32 v198, 0x3b808081, v235
	v_mul_f32_e32 v149, v130, v3
	v_mul_f32_e32 v3, 0x3b808081, v228
	v_mul_f32_e32 v179, v131, v157
	v_mul_f32_e32 v157, 0x3b808081, v229
	v_mul_f32_e32 v189, v132, v169
	v_mul_f32_e32 v169, 0x3b808081, v230
	v_mul_f32_e32 v213, v133, v198
	v_mul_f32_e32 v198, 0x3b808081, v231
	v_mul_f32_e32 v3, v126, v3
	v_mul_f32_e32 v157, v127, v157
	v_mul_f32_e32 v169, v128, v169
	v_mul_f32_e32 v203, v129, v198
	s_and_b64 vcc, exec, s[36:37]
	s_cbranch_vccz .LBB0_757
	s_ashr_i32 s65, s64, 31
	s_lshl_b64 s[0:1], s[64:65], 21
	s_add_u32 s0, s77, s0
	s_addc_u32 s1, s78, s1
	v_lshlrev_b64 v[198:199], 12, v[220:221]
	v_lshl_add_u64 v[198:199], s[0:1], 0, v[198:199]
	v_lshl_add_u64 v[198:199], v[4:5], 1, v[198:199]
	v_add_co_u32_e32 v198, vcc, 0xfe000000, v198
	v_cvt_pk_bf16_f32 v238, v149, v179
	v_cvt_pk_bf16_f32 v239, v189, v213
	v_cvt_pk_bf16_f32 v240, v3, v157
	v_cvt_pk_bf16_f32 v241, v169, v203
	s_nop 1
	v_addc_co_u32_e32 v199, vcc, -1, v199, vcc
	global_store_dwordx4 v[198:199], v[238:241], off
	s_mov_b64 s[14:15], 0

.LBB0_1137:
	s_add_u32 s0, s36, 0xfff80080
	s_addc_u32 s6, s37, -1
	s_add_i32 s49, 0, 0x10000
	s_cmp_eq_u32 s66, 28
	s_cselect_b32 s35, s29, s6
	s_cselect_b32 s34, s64, s0
	v_add_u32_e32 v156, s49, v157
	s_cselect_b32 s31, s23, s39
	s_cselect_b32 s30, s65, s38
	s_add_i32 s0, 0, 0x14000
	ds_read_b128 v[144:147], v156
	ds_read_b128 v[148:151], v156 offset:1024
	ds_read_b128 v[152:155], v156 offset:2048
	ds_read_b128 v[162:165], v156 offset:3072
	v_add_u32_e32 v156, s0, v157
	ds_read_b128 v[166:169], v156
	ds_read_b128 v[170:173], v156 offset:1024
	ds_read_b128 v[174:177], v156 offset:2048
	ds_read_b128 v[178:181], v156 offset:3072
	v_lshl_add_u64 v[194:195], s[36:37], 0, v[140:141]
	s_add_i32 m0, s33, 0xc000
	ds_read_b128 v[182:185], v161
	ds_read_b128 v[186:189], v161 offset:1024
	ds_read_b128 v[190:193], v161 offset:2048
	ds_read_b128 v[200:203], v161 offset:3072
	ds_read_b128 v[204:207], v161 offset:4096
	ds_read_b128 v[208:211], v161 offset:5120
	ds_read_b128 v[212:215], v161 offset:6144
	ds_read_b128 v[216:219], v161 offset:7168
	global_load_lds_dwordx4 v[194:195], off
	s_add_i32 m0, s33, 0xe000
	v_lshl_add_u64 v[194:195], s[36:37], 0, v[142:143]
	global_load_lds_dwordx4 v[194:195], off
	s_setprio 1
	s_waitcnt vmcnt(8) lgkmcnt(0)
	s_barrier
	v_mfma_f32_16x16x32_bf16 v[128:131], v[144:147], v[182:185], v[128:131]
	v_mfma_f32_16x16x32_bf16 v[124:127], v[152:155], v[182:185], v[124:127]
	v_mfma_f32_16x16x32_bf16 v[112:115], v[144:147], v[190:193], v[112:115]
	v_mfma_f32_16x16x32_bf16 v[108:111], v[152:155], v[190:193], v[108:111]
	v_mfma_f32_16x16x32_bf16 v[96:99], v[144:147], v[204:207], v[96:99]
	v_mfma_f32_16x16x32_bf16 v[92:95], v[152:155], v[204:207], v[92:95]
	v_mfma_f32_16x16x32_bf16 v[80:83], v[144:147], v[212:215], v[80:83]
	v_mfma_f32_16x16x32_bf16 v[76:79], v[152:155], v[212:215], v[76:79]
	v_mfma_f32_16x16x32_bf16 v[128:131], v[148:151], v[186:189], v[128:131]
	v_mfma_f32_16x16x32_bf16 v[124:127], v[162:165], v[186:189], v[124:127]
	v_mfma_f32_16x16x32_bf16 v[112:115], v[148:151], v[200:203], v[112:115]
	v_mfma_f32_16x16x32_bf16 v[108:111], v[162:165], v[200:203], v[108:111]
	v_mfma_f32_16x16x32_bf16 v[96:99], v[148:151], v[208:211], v[96:99]
	v_mfma_f32_16x16x32_bf16 v[92:95], v[162:165], v[208:211], v[92:95]
	v_mfma_f32_16x16x32_bf16 v[80:83], v[148:151], v[216:219], v[80:83]
	v_mfma_f32_16x16x32_bf16 v[76:79], v[162:165], v[216:219], v[76:79]
	s_setprio 0
	s_setprio 1
	v_mfma_f32_16x16x32_bf16 v[120:123], v[166:169], v[182:185], v[120:123]
	v_mfma_f32_16x16x32_bf16 v[116:119], v[174:177], v[182:185], v[116:119]
	v_mfma_f32_16x16x32_bf16 v[104:107], v[166:169], v[190:193], v[104:107]
	v_mfma_f32_16x16x32_bf16 v[100:103], v[174:177], v[190:193], v[100:103]
	v_mfma_f32_16x16x32_bf16 v[88:91], v[166:169], v[204:207], v[88:91]
	v_mfma_f32_16x16x32_bf16 v[84:87], v[174:177], v[204:207], v[84:87]
	v_mfma_f32_16x16x32_bf16 v[72:75], v[166:169], v[212:215], v[72:75]
	v_mfma_f32_16x16x32_bf16 v[68:71], v[174:177], v[212:215], v[68:71]
	v_mfma_f32_16x16x32_bf16 v[120:123], v[170:173], v[186:189], v[120:123]
	v_mfma_f32_16x16x32_bf16 v[116:119], v[178:181], v[186:189], v[116:119]
	v_mfma_f32_16x16x32_bf16 v[104:107], v[170:173], v[200:203], v[104:107]
	v_mfma_f32_16x16x32_bf16 v[100:103], v[178:181], v[200:203], v[100:103]
	v_mfma_f32_16x16x32_bf16 v[88:91], v[170:173], v[208:211], v[88:91]
	v_mfma_f32_16x16x32_bf16 v[84:87], v[178:181], v[208:211], v[84:87]
	v_mfma_f32_16x16x32_bf16 v[72:75], v[170:173], v[216:219], v[72:75]
	v_mfma_f32_16x16x32_bf16 v[68:71], v[178:181], v[216:219], v[68:71]
	s_barrier
	s_setprio 0
	s_add_i32 s6, s49, s25
	v_lshl_add_u64 v[194:195], s[30:31], 0, v[136:137]
	s_mov_b32 m0, s6
	ds_read_b128 v[182:185], v161 offset:16384
	ds_read_b128 v[186:189], v161 offset:17408
	ds_read_b128 v[190:193], v161 offset:18432
	ds_read_b128 v[200:203], v161 offset:19456
	ds_read_b128 v[204:207], v161 offset:20480
	ds_read_b128 v[208:211], v161 offset:21504
	ds_read_b128 v[212:215], v161 offset:22528
	ds_read_b128 v[216:219], v161 offset:23552
	global_load_lds_dwordx4 v[194:195], off
	s_add_i32 m0, s6, 0x2000
	s_add_u32 s68, s30, 0x80000
	v_lshl_add_u64 v[198:199], s[30:31], 0, v[132:133]
	s_addc_u32 s69, s31, 0
	s_add_i32 s0, s0, s25
	global_load_lds_dwordx4 v[198:199], off
	v_lshl_add_u64 v[220:221], s[68:69], 0, v[136:137]
	s_mov_b32 m0, s0
	global_load_lds_dwordx4 v[220:221], off
	s_add_i32 m0, s0, 0x2000
	v_lshl_add_u64 v[220:221], s[68:69], 0, v[132:133]
	global_load_lds_dwordx4 v[220:221], off
	s_mov_b32 m0, s33
	v_lshl_add_u64 v[220:221], s[34:35], 0, v[138:139]
	global_load_lds_dwordx4 v[220:221], off
	s_mov_b32 m0, s40
	v_lshl_add_u64 v[222:223], s[34:35], 0, v[134:135]
	global_load_lds_dwordx4 v[222:223], off
	s_setprio 1
	s_waitcnt vmcnt(8) lgkmcnt(0)
	s_barrier
	v_mfma_f32_16x16x32_bf16 v[64:67], v[144:147], v[182:185], v[64:67]
	v_mfma_f32_16x16x32_bf16 v[60:63], v[152:155], v[182:185], v[60:63]
	v_mfma_f32_16x16x32_bf16 v[48:51], v[144:147], v[190:193], v[48:51]
	v_mfma_f32_16x16x32_bf16 v[44:47], v[152:155], v[190:193], v[44:47]
	v_mfma_f32_16x16x32_bf16 v[32:35], v[144:147], v[204:207], v[32:35]
	v_mfma_f32_16x16x32_bf16 v[28:31], v[152:155], v[204:207], v[28:31]
	v_mfma_f32_16x16x32_bf16 v[16:19], v[144:147], v[212:215], v[16:19]
	v_mfma_f32_16x16x32_bf16 v[12:15], v[152:155], v[212:215], v[12:15]
	v_mfma_f32_16x16x32_bf16 v[64:67], v[148:151], v[186:189], v[64:67]
	v_mfma_f32_16x16x32_bf16 v[60:63], v[162:165], v[186:189], v[60:63]
	v_mfma_f32_16x16x32_bf16 v[48:51], v[148:151], v[200:203], v[48:51]
	v_mfma_f32_16x16x32_bf16 v[44:47], v[162:165], v[200:203], v[44:47]
	v_mfma_f32_16x16x32_bf16 v[32:35], v[148:151], v[208:211], v[32:35]
	v_mfma_f32_16x16x32_bf16 v[28:31], v[162:165], v[208:211], v[28:31]
	v_mfma_f32_16x16x32_bf16 v[16:19], v[148:151], v[216:219], v[16:19]
	v_mfma_f32_16x16x32_bf16 v[12:15], v[162:165], v[216:219], v[12:15]
	s_setprio 0
	s_setprio 1
	v_mfma_f32_16x16x32_bf16 v[56:59], v[166:169], v[182:185], v[56:59]
	v_mfma_f32_16x16x32_bf16 v[52:55], v[174:177], v[182:185], v[52:55]
	v_mfma_f32_16x16x32_bf16 v[40:43], v[166:169], v[190:193], v[40:43]
	v_mfma_f32_16x16x32_bf16 v[36:39], v[174:177], v[190:193], v[36:39]
	v_mfma_f32_16x16x32_bf16 v[24:27], v[166:169], v[204:207], v[24:27]
	v_mfma_f32_16x16x32_bf16 v[20:23], v[174:177], v[204:207], v[20:23]
	v_mfma_f32_16x16x32_bf16 v[8:11], v[166:169], v[212:215], v[8:11]
	v_mfma_f32_16x16x32_bf16 v[4:7], v[174:177], v[212:215], v[4:7]
	v_mfma_f32_16x16x32_bf16 v[56:59], v[170:173], v[186:189], v[56:59]
	v_mfma_f32_16x16x32_bf16 v[52:55], v[178:181], v[186:189], v[52:55]
	v_mfma_f32_16x16x32_bf16 v[40:43], v[170:173], v[200:203], v[40:43]
	v_mfma_f32_16x16x32_bf16 v[36:39], v[178:181], v[200:203], v[36:39]
	v_mfma_f32_16x16x32_bf16 v[24:27], v[170:173], v[208:211], v[24:27]
	v_mfma_f32_16x16x32_bf16 v[20:23], v[178:181], v[208:211], v[20:23]
	v_mfma_f32_16x16x32_bf16 v[8:11], v[170:173], v[216:219], v[8:11]
	v_mfma_f32_16x16x32_bf16 v[4:7], v[178:181], v[216:219], v[4:7]
	s_barrier
	s_setprio 0
	s_add_i32 s0, 0, 0x18000
	v_add_u32_e32 v156, s0, v157
	s_add_i32 s6, 0, 0x1c000
	ds_read_b128 v[144:147], v156
	ds_read_b128 v[148:151], v156 offset:1024
	ds_read_b128 v[152:155], v156 offset:2048
	ds_read_b128 v[162:165], v156 offset:3072
	v_add_u32_e32 v156, s6, v157
	ds_read_b128 v[166:169], v156
	ds_read_b128 v[170:173], v156 offset:1024
	ds_read_b128 v[174:177], v156 offset:2048
	ds_read_b128 v[178:181], v156 offset:3072
	s_add_u32 s34, s34, 0x80000
	s_addc_u32 s35, s35, 0
	s_mov_b32 m0, s50
	v_lshl_add_u64 v[224:225], s[34:35], 0, v[138:139]
	ds_read_b128 v[182:185], v161 offset:32768
	ds_read_b128 v[186:189], v161 offset:33792
	ds_read_b128 v[190:193], v161 offset:34816
	ds_read_b128 v[200:203], v161 offset:35840
	ds_read_b128 v[204:207], v161 offset:36864
	ds_read_b128 v[208:211], v161 offset:37888
	ds_read_b128 v[212:215], v161 offset:38912
	ds_read_b128 v[216:219], v161 offset:39936
	global_load_lds_dwordx4 v[224:225], off
	s_mov_b32 m0, s51
	v_lshl_add_u64 v[224:225], s[34:35], 0, v[134:135]
	global_load_lds_dwordx4 v[224:225], off
	s_setprio 1
	s_waitcnt vmcnt(8) lgkmcnt(0)
	s_barrier
	v_mfma_f32_16x16x32_bf16 v[128:131], v[144:147], v[182:185], v[128:131]
	v_mfma_f32_16x16x32_bf16 v[124:127], v[152:155], v[182:185], v[124:127]
	v_mfma_f32_16x16x32_bf16 v[112:115], v[144:147], v[190:193], v[112:115]
	v_mfma_f32_16x16x32_bf16 v[108:111], v[152:155], v[190:193], v[108:111]
	v_mfma_f32_16x16x32_bf16 v[96:99], v[144:147], v[204:207], v[96:99]
	v_mfma_f32_16x16x32_bf16 v[92:95], v[152:155], v[204:207], v[92:95]
	v_mfma_f32_16x16x32_bf16 v[80:83], v[144:147], v[212:215], v[80:83]
	v_mfma_f32_16x16x32_bf16 v[76:79], v[152:155], v[212:215], v[76:79]
	v_mfma_f32_16x16x32_bf16 v[128:131], v[148:151], v[186:189], v[128:131]
	v_mfma_f32_16x16x32_bf16 v[124:127], v[162:165], v[186:189], v[124:127]
	v_mfma_f32_16x16x32_bf16 v[112:115], v[148:151], v[200:203], v[112:115]
	v_mfma_f32_16x16x32_bf16 v[108:111], v[162:165], v[200:203], v[108:111]
	v_mfma_f32_16x16x32_bf16 v[96:99], v[148:151], v[208:211], v[96:99]
	v_mfma_f32_16x16x32_bf16 v[92:95], v[162:165], v[208:211], v[92:95]
	v_mfma_f32_16x16x32_bf16 v[80:83], v[148:151], v[216:219], v[80:83]
	v_mfma_f32_16x16x32_bf16 v[76:79], v[162:165], v[216:219], v[76:79]
	s_setprio 0
	s_setprio 1
	v_mfma_f32_16x16x32_bf16 v[120:123], v[166:169], v[182:185], v[120:123]
	v_mfma_f32_16x16x32_bf16 v[116:119], v[174:177], v[182:185], v[116:119]
	v_mfma_f32_16x16x32_bf16 v[104:107], v[166:169], v[190:193], v[104:107]
	v_mfma_f32_16x16x32_bf16 v[100:103], v[174:177], v[190:193], v[100:103]
	v_mfma_f32_16x16x32_bf16 v[88:91], v[166:169], v[204:207], v[88:91]
	v_mfma_f32_16x16x32_bf16 v[84:87], v[174:177], v[204:207], v[84:87]
	v_mfma_f32_16x16x32_bf16 v[72:75], v[166:169], v[212:215], v[72:75]
	v_mfma_f32_16x16x32_bf16 v[68:71], v[174:177], v[212:215], v[68:71]
	v_mfma_f32_16x16x32_bf16 v[120:123], v[170:173], v[186:189], v[120:123]
	v_mfma_f32_16x16x32_bf16 v[116:119], v[178:181], v[186:189], v[116:119]
	v_mfma_f32_16x16x32_bf16 v[104:107], v[170:173], v[200:203], v[104:107]
	v_mfma_f32_16x16x32_bf16 v[100:103], v[178:181], v[200:203], v[100:103]
	v_mfma_f32_16x16x32_bf16 v[88:91], v[170:173], v[208:211], v[88:91]
	v_mfma_f32_16x16x32_bf16 v[84:87], v[178:181], v[208:211], v[84:87]
	v_mfma_f32_16x16x32_bf16 v[72:75], v[170:173], v[216:219], v[72:75]
	v_mfma_f32_16x16x32_bf16 v[68:71], v[178:181], v[216:219], v[68:71]
	s_barrier
	s_setprio 0
	s_add_i32 s0, s0, s25
	v_lshl_add_u64 v[194:195], v[194:195], 0, s[90:91]
	s_mov_b32 m0, s0
	ds_read_b128 v[182:185], v161 offset:49152
	ds_read_b128 v[186:189], v161 offset:50176
	ds_read_b128 v[190:193], v161 offset:51200
	ds_read_b128 v[200:203], v161 offset:52224
	ds_read_b128 v[204:207], v161 offset:53248
	ds_read_b128 v[208:211], v161 offset:54272
	ds_read_b128 v[212:215], v161 offset:55296
	ds_read_b128 v[216:219], v161 offset:56320
	global_load_lds_dwordx4 v[194:195], off
	s_add_i32 m0, s0, 0x2000
	s_add_u32 s30, s30, 0x80080
	v_lshl_add_u64 v[194:195], v[198:199], 0, s[90:91]
	s_addc_u32 s31, s31, 0
	s_add_i32 s0, s6, s25
	global_load_lds_dwordx4 v[194:195], off
	s_mov_b32 m0, s0
	v_lshl_add_u64 v[194:195], s[30:31], 0, v[136:137]
	global_load_lds_dwordx4 v[194:195], off
	s_add_i32 m0, s0, 0x2000
	v_lshl_add_u64 v[194:195], s[30:31], 0, v[132:133]
	global_load_lds_dwordx4 v[194:195], off
	s_mov_b32 m0, s55
	v_lshl_add_u64 v[194:195], v[220:221], 0, s[90:91]
	global_load_lds_dwordx4 v[194:195], off
	s_mov_b32 m0, s60
	v_lshl_add_u64 v[194:195], v[222:223], 0, s[90:91]
	global_load_lds_dwordx4 v[194:195], off
	s_setprio 1
	s_waitcnt vmcnt(8) lgkmcnt(0)
	s_barrier
	v_mfma_f32_16x16x32_bf16 v[64:67], v[144:147], v[182:185], v[64:67]
	v_mfma_f32_16x16x32_bf16 v[60:63], v[152:155], v[182:185], v[60:63]
	v_mfma_f32_16x16x32_bf16 v[48:51], v[144:147], v[190:193], v[48:51]
	v_mfma_f32_16x16x32_bf16 v[44:47], v[152:155], v[190:193], v[44:47]
	v_mfma_f32_16x16x32_bf16 v[32:35], v[144:147], v[204:207], v[32:35]
	v_mfma_f32_16x16x32_bf16 v[28:31], v[152:155], v[204:207], v[28:31]
	v_mfma_f32_16x16x32_bf16 v[16:19], v[144:147], v[212:215], v[16:19]
	v_mfma_f32_16x16x32_bf16 v[12:15], v[152:155], v[212:215], v[12:15]
	v_mfma_f32_16x16x32_bf16 v[64:67], v[148:151], v[186:189], v[64:67]
	v_mfma_f32_16x16x32_bf16 v[60:63], v[162:165], v[186:189], v[60:63]
	v_mfma_f32_16x16x32_bf16 v[48:51], v[148:151], v[200:203], v[48:51]
	v_mfma_f32_16x16x32_bf16 v[44:47], v[162:165], v[200:203], v[44:47]
	v_mfma_f32_16x16x32_bf16 v[32:35], v[148:151], v[208:211], v[32:35]
	v_mfma_f32_16x16x32_bf16 v[28:31], v[162:165], v[208:211], v[28:31]
	v_mfma_f32_16x16x32_bf16 v[16:19], v[148:151], v[216:219], v[16:19]
	v_mfma_f32_16x16x32_bf16 v[12:15], v[162:165], v[216:219], v[12:15]
	s_setprio 0
	s_setprio 1
	v_mfma_f32_16x16x32_bf16 v[56:59], v[166:169], v[182:185], v[56:59]
	v_mfma_f32_16x16x32_bf16 v[52:55], v[174:177], v[182:185], v[52:55]
	v_mfma_f32_16x16x32_bf16 v[40:43], v[166:169], v[190:193], v[40:43]
	v_mfma_f32_16x16x32_bf16 v[36:39], v[174:177], v[190:193], v[36:39]
	v_mfma_f32_16x16x32_bf16 v[24:27], v[166:169], v[204:207], v[24:27]
	v_mfma_f32_16x16x32_bf16 v[20:23], v[174:177], v[204:207], v[20:23]
	v_mfma_f32_16x16x32_bf16 v[8:11], v[166:169], v[212:215], v[8:11]
	v_mfma_f32_16x16x32_bf16 v[4:7], v[174:177], v[212:215], v[4:7]
	v_mfma_f32_16x16x32_bf16 v[56:59], v[170:173], v[186:189], v[56:59]
	v_mfma_f32_16x16x32_bf16 v[52:55], v[178:181], v[186:189], v[52:55]
	v_mfma_f32_16x16x32_bf16 v[40:43], v[170:173], v[200:203], v[40:43]
	v_mfma_f32_16x16x32_bf16 v[36:39], v[178:181], v[200:203], v[36:39]
	v_mfma_f32_16x16x32_bf16 v[24:27], v[170:173], v[208:211], v[24:27]
	v_mfma_f32_16x16x32_bf16 v[20:23], v[178:181], v[208:211], v[20:23]
	v_mfma_f32_16x16x32_bf16 v[8:11], v[170:173], v[216:219], v[8:11]
	v_mfma_f32_16x16x32_bf16 v[4:7], v[178:181], v[216:219], v[4:7]
	s_barrier
	s_setprio 0
	s_add_i32 s66, s66, 2
	s_add_u32 s36, s36, 0x100
	s_addc_u32 s37, s37, 0
	s_add_u32 s38, s38, 0x100
	s_addc_u32 s39, s39, 0
	s_cmp_gt_u32 s66, 29
	s_cbranch_scc0 .LBB0_1137
	s_and_b64 vcc, exec, s[20:21]
	s_mov_b32 s100, 0
	s_cbranch_vccz .LBB0_1140
	s_mov_b32 s100, 1
.LBB0_1140:
	v_lshl_add_u32 v150, s63, 8, v3
	v_ashrrev_i32_e32 v151, 31, v150
	v_lshl_add_u64 v[164:165], v[150:151], 3, s[16:17]
	global_load_dwordx2 v[168:169], v[164:165], off
	v_or_b32_e32 v148, 16, v150
	v_ashrrev_i32_e32 v149, 31, v148
	v_lshl_add_u64 v[144:145], v[148:149], 3, s[16:17]
	global_load_dwordx2 v[172:173], v[144:145], off
	v_or_b32_e32 v146, 32, v150
	v_ashrrev_i32_e32 v147, 31, v146
	v_lshl_add_u64 v[144:145], v[146:147], 3, s[16:17]
	global_load_dwordx2 v[174:175], v[144:145], off
	global_load_dwordx2 v[162:163], v[164:165], off offset:1152
	v_or_b32_e32 v144, 48, v150
	v_ashrrev_i32_e32 v145, 31, v144
	v_lshl_add_u64 v[152:153], v[144:145], 3, s[16:17]
	global_load_dwordx2 v[154:155], v[152:153], off
	global_load_dwordx2 v[166:167], v[164:165], off offset:1280
	v_mov_b32_e32 v177, v2
	global_load_dwordx2 v[152:153], v[164:165], off offset:1024
	s_min_u32 s23, s72, 32
	global_load_dwordx2 v[164:165], v[164:165], off offset:1408
	s_sub_i32 s29, 32, s23
	v_add_u32_e32 v170, 0x80, v150
	v_add_u32_e32 v149, 0x90, v150
	v_add_u32_e32 v147, 0xa0, v150
	v_add_u32_e32 v145, 0xb0, v150
	s_andn2_b64 vcc, exec, s[10:11]
	s_cmp_eq_u32 s100, 0
	s_cbranch_scc1 .Lx_ab_5
	s_barrier
.Lx_ab_5:
	s_waitcnt vmcnt(0)
	v_mov_b32_e32 v176, v169
	v_lshlrev_b64 v[176:177], s23, v[176:177]
	v_min_u32_e32 v151, 1, v176
	v_or_b32_e32 v151, v177, v151
	v_cvt_f32_u32_e32 v151, v151
	v_cvt_f32_u32_e32 v156, v168
	v_mov_b32_e32 v168, v173
	v_mov_b32_e32 v169, v2
	v_ldexp_f32 v151, v151, s29
	v_mul_f32_e32 v151, 0x43800000, v151
	v_fmac_f32_e32 v151, 0x33800000, v156
	v_fmamk_f32 v151, v151, 0x3a000000, v1
	v_lshlrev_b64 v[168:169], s23, v[168:169]
	v_rsq_f32_e32 v160, v151
	v_min_u32_e32 v151, 1, v168
	v_or_b32_e32 v151, v169, v151
	v_cvt_f32_u32_e32 v151, v151
	v_cvt_f32_u32_e32 v156, v172
	v_mov_b32_e32 v168, v175
	v_mov_b32_e32 v169, v2
	v_ldexp_f32 v151, v151, s29
	v_mul_f32_e32 v151, 0x43800000, v151
	v_fmac_f32_e32 v151, 0x33800000, v156
	v_fmamk_f32 v151, v151, 0x3a000000, v1
	v_lshlrev_b64 v[168:169], s23, v[168:169]
	v_rsq_f32_e32 v158, v151
	v_min_u32_e32 v151, 1, v168
	v_or_b32_e32 v151, v169, v151
	v_cvt_f32_u32_e32 v151, v151
	v_cvt_f32_u32_e32 v156, v174
	v_mov_b32_e32 v168, v155
	v_mov_b32_e32 v169, v2
	v_ldexp_f32 v151, v151, s29
	v_mul_f32_e32 v151, 0x43800000, v151
	v_fmac_f32_e32 v151, 0x33800000, v156
	v_fmamk_f32 v151, v151, 0x3a000000, v1
	v_lshlrev_b64 v[168:169], s23, v[168:169]
	v_rsq_f32_e32 v156, v151
	v_min_u32_e32 v151, 1, v168
	v_or_b32_e32 v151, v169, v151
	v_cvt_f32_u32_e32 v151, v151
	v_cvt_f32_u32_e32 v154, v154
	v_mov_b32_e32 v168, v153
	v_mov_b32_e32 v169, v2
	v_ldexp_f32 v151, v151, s29
	v_mul_f32_e32 v151, 0x43800000, v151
	v_fmac_f32_e32 v151, 0x33800000, v154
	v_fmamk_f32 v151, v151, 0x3a000000, v1
	v_lshlrev_b64 v[168:169], s23, v[168:169]
	v_rsq_f32_e32 v154, v151
	v_min_u32_e32 v151, 1, v168
	v_or_b32_e32 v151, v169, v151
	v_cvt_f32_u32_e32 v151, v151
	v_cvt_f32_u32_e32 v152, v152
	v_mov_b32_e32 v168, v163
	v_mov_b32_e32 v169, v2
	v_ldexp_f32 v151, v151, s29
	v_mul_f32_e32 v151, 0x43800000, v151
	v_fmac_f32_e32 v151, 0x33800000, v152
	v_fmamk_f32 v151, v151, 0x3a000000, v1
	v_lshlrev_b64 v[168:169], s23, v[168:169]
	v_rsq_f32_e32 v152, v151
	v_min_u32_e32 v151, 1, v168
	v_or_b32_e32 v151, v169, v151
	v_cvt_f32_u32_e32 v151, v151
	v_cvt_f32_u32_e32 v153, v162
	v_mov_b32_e32 v168, v167
	v_mov_b32_e32 v169, v2
	v_ldexp_f32 v151, v151, s29
	v_mul_f32_e32 v151, 0x43800000, v151
	v_fmac_f32_e32 v151, 0x33800000, v153
	v_fmamk_f32 v151, v151, 0x3a000000, v1
	v_lshlrev_b64 v[168:169], s23, v[168:169]
	v_rsq_f32_e32 v162, v151
	v_min_u32_e32 v151, 1, v168
	v_or_b32_e32 v151, v169, v151
	v_cvt_f32_u32_e32 v151, v151
	v_cvt_f32_u32_e32 v153, v166
	v_mov_b32_e32 v168, v165
	v_mov_b32_e32 v169, v2
	v_ldexp_f32 v151, v151, s29
	v_mul_f32_e32 v151, 0x43800000, v151
	v_fmac_f32_e32 v151, 0x33800000, v153
	v_fmamk_f32 v151, v151, 0x3a000000, v1
	v_lshlrev_b64 v[168:169], s23, v[168:169]
	v_rsq_f32_e32 v166, v151
	v_min_u32_e32 v151, 1, v168
	v_or_b32_e32 v151, v169, v151
	v_cvt_f32_u32_e32 v151, v151
	v_cvt_f32_u32_e32 v153, v164
	v_pk_mul_f32 v[124:125], v[124:125], v[160:161] op_sel_hi:[1,0]
	v_lshl_or_b32 v172, s62, 8, v159
	v_ldexp_f32 v151, v151, s29
	v_mul_f32_e32 v151, 0x43800000, v151
	v_fmac_f32_e32 v151, 0x33800000, v153
	v_pk_mul_f32 v[128:129], v[128:129], v[160:161] op_sel_hi:[1,0]
	v_pk_mul_f32 v[126:127], v[126:127], v[160:161] op_sel_hi:[1,0]
	v_max_f32_e32 v124, 0, v124
	v_fmamk_f32 v151, v151, 0x3a000000, v1
	v_ashrrev_i32_e32 v173, 31, v172
	v_mov_b64_e32 v[168:169], s[14:15]
	v_pk_mul_f32 v[130:131], v[130:131], v[160:161] op_sel_hi:[1,0]
	v_mul_f32_e32 v153, v124, v124
	v_max_f32_e32 v124, 0, v129
	v_max_f32_e32 v125, 0, v125
	v_max_f32_e32 v126, 0, v126
	v_rsq_f32_e32 v164, v151
	v_mad_i64_i32 v[174:175], s[30:31], v150, s48, v[168:169]
	v_lshlrev_b64 v[150:151], 1, v[172:173]
	v_max_f32_e32 v128, 0, v128
	v_mul_f32_e32 v124, v124, v124
	v_mul_f32_e32 v129, v125, v125
	v_max_f32_e32 v125, 0, v130
	v_mul_f32_e32 v130, v126, v126
	v_max_f32_e32 v126, 0, v131
	v_max_f32_e32 v127, 0, v127
	v_pk_mul_f32 v[118:119], v[118:119], v[160:161] op_sel_hi:[1,0]
	v_pk_mul_f32 v[116:117], v[116:117], v[160:161] op_sel_hi:[1,0]
	v_lshl_add_u64 v[172:173], v[174:175], 0, v[150:151]
	v_mul_f32_e32 v128, v128, v128
	v_mul_f32_e32 v125, v125, v125
	v_mul_f32_e32 v126, v126, v126
	v_mul_f32_e32 v127, v127, v127
	v_cvt_pk_bf16_f32 v124, v128, v124
	v_pk_mul_f32 v[122:123], v[122:123], v[160:161] op_sel_hi:[1,0]
	v_pk_mul_f32 v[120:121], v[120:121], v[160:161] op_sel_hi:[1,0]
	v_max_f32_e32 v116, 0, v116
	v_max_f32_e32 v117, 0, v117
	v_max_f32_e32 v118, 0, v118
	v_cvt_pk_bf16_f32 v125, v125, v126
	v_cvt_pk_bf16_f32 v126, v153, v129
	v_cvt_pk_bf16_f32 v127, v130, v127
	global_store_dwordx4 v[172:173], v[124:127], off
	v_max_f32_e32 v120, 0, v120
	v_max_f32_e32 v119, 0, v119
	v_mul_f32_e32 v124, v116, v116
	v_max_f32_e32 v116, 0, v121
	v_mul_f32_e32 v121, v117, v117
	v_max_f32_e32 v117, 0, v122
	v_mul_f32_e32 v122, v118, v118
	v_max_f32_e32 v118, 0, v123
	v_mul_f32_e32 v116, v116, v116
	v_mul_f32_e32 v117, v117, v117
	v_mul_f32_e32 v118, v118, v118
	v_pk_mul_f32 v[108:109], v[108:109], v[158:159] op_sel_hi:[1,0]
	v_mul_f32_e32 v120, v120, v120
	v_mul_f32_e32 v119, v119, v119
	v_cvt_pk_bf16_f32 v116, v120, v116
	v_cvt_pk_bf16_f32 v117, v117, v118
	v_cvt_pk_bf16_f32 v118, v124, v121
	v_pk_mul_f32 v[112:113], v[112:113], v[158:159] op_sel_hi:[1,0]
	v_pk_mul_f32 v[110:111], v[110:111], v[158:159] op_sel_hi:[1,0]
	v_max_f32_e32 v108, 0, v108
	v_cvt_pk_bf16_f32 v119, v122, v119
	global_store_dwordx4 v[172:173], v[116:119], off offset:256
	v_pk_mul_f32 v[114:115], v[114:115], v[158:159] op_sel_hi:[1,0]
	v_max_f32_e32 v109, 0, v109
	v_mul_f32_e32 v118, v108, v108
	v_max_f32_e32 v108, 0, v113
	v_max_f32_e32 v110, 0, v110
	v_mad_i64_i32 v[116:117], s[30:31], v148, s48, v[168:169]
	v_max_f32_e32 v112, 0, v112
	v_mul_f32_e32 v108, v108, v108
	v_mul_f32_e32 v113, v109, v109
	v_max_f32_e32 v109, 0, v114
	v_mul_f32_e32 v114, v110, v110
	v_max_f32_e32 v110, 0, v115
	v_max_f32_e32 v111, 0, v111
	v_pk_mul_f32 v[102:103], v[102:103], v[158:159] op_sel_hi:[1,0]
	v_pk_mul_f32 v[100:101], v[100:101], v[158:159] op_sel_hi:[1,0]
	v_lshl_add_u64 v[116:117], v[116:117], 0, v[150:151]
	v_mul_f32_e32 v112, v112, v112
	v_mul_f32_e32 v109, v109, v109
	v_mul_f32_e32 v110, v110, v110
	v_mul_f32_e32 v111, v111, v111
	v_cvt_pk_bf16_f32 v108, v112, v108
	v_pk_mul_f32 v[106:107], v[106:107], v[158:159] op_sel_hi:[1,0]
	v_pk_mul_f32 v[104:105], v[104:105], v[158:159] op_sel_hi:[1,0]
	v_max_f32_e32 v100, 0, v100
	v_max_f32_e32 v101, 0, v101
	v_max_f32_e32 v102, 0, v102
	v_cvt_pk_bf16_f32 v109, v109, v110
	v_cvt_pk_bf16_f32 v110, v118, v113
	v_cvt_pk_bf16_f32 v111, v114, v111
	global_store_dwordx4 v[116:117], v[108:111], off
	v_max_f32_e32 v104, 0, v104
	v_max_f32_e32 v103, 0, v103
	v_mul_f32_e32 v108, v100, v100
	v_max_f32_e32 v100, 0, v105
	v_mul_f32_e32 v105, v101, v101
	v_max_f32_e32 v101, 0, v106
	v_mul_f32_e32 v106, v102, v102
	v_max_f32_e32 v102, 0, v107
	v_mul_f32_e32 v100, v100, v100
	v_mul_f32_e32 v101, v101, v101
	v_mul_f32_e32 v102, v102, v102
	v_pk_mul_f32 v[92:93], v[92:93], v[156:157] op_sel_hi:[1,0]
	v_mul_f32_e32 v104, v104, v104
	v_mul_f32_e32 v103, v103, v103
	v_cvt_pk_bf16_f32 v100, v104, v100
	v_cvt_pk_bf16_f32 v101, v101, v102
	v_cvt_pk_bf16_f32 v102, v108, v105
	v_pk_mul_f32 v[96:97], v[96:97], v[156:157] op_sel_hi:[1,0]
	v_pk_mul_f32 v[94:95], v[94:95], v[156:157] op_sel_hi:[1,0]
	v_max_f32_e32 v92, 0, v92
	v_cvt_pk_bf16_f32 v103, v106, v103
	global_store_dwordx4 v[116:117], v[100:103], off offset:256
	v_pk_mul_f32 v[98:99], v[98:99], v[156:157] op_sel_hi:[1,0]
	v_max_f32_e32 v93, 0, v93
	v_mul_f32_e32 v102, v92, v92
	v_max_f32_e32 v92, 0, v97
	v_max_f32_e32 v94, 0, v94
	v_mad_i64_i32 v[100:101], s[30:31], v146, s48, v[168:169]
	v_max_f32_e32 v96, 0, v96
	v_mul_f32_e32 v92, v92, v92
	v_mul_f32_e32 v97, v93, v93
	v_max_f32_e32 v93, 0, v98
	v_mul_f32_e32 v98, v94, v94
	v_max_f32_e32 v94, 0, v99
	v_max_f32_e32 v95, 0, v95
	v_pk_mul_f32 v[86:87], v[86:87], v[156:157] op_sel_hi:[1,0]
	v_pk_mul_f32 v[84:85], v[84:85], v[156:157] op_sel_hi:[1,0]
	v_lshl_add_u64 v[100:101], v[100:101], 0, v[150:151]
	v_mul_f32_e32 v96, v96, v96
	v_mul_f32_e32 v93, v93, v93
	v_mul_f32_e32 v94, v94, v94
	v_mul_f32_e32 v95, v95, v95
	v_cvt_pk_bf16_f32 v92, v96, v92
	v_pk_mul_f32 v[90:91], v[90:91], v[156:157] op_sel_hi:[1,0]
	v_pk_mul_f32 v[88:89], v[88:89], v[156:157] op_sel_hi:[1,0]
	v_max_f32_e32 v84, 0, v84
	v_max_f32_e32 v85, 0, v85
	v_max_f32_e32 v86, 0, v86
	v_cvt_pk_bf16_f32 v93, v93, v94
	v_cvt_pk_bf16_f32 v94, v102, v97
	v_cvt_pk_bf16_f32 v95, v98, v95
	global_store_dwordx4 v[100:101], v[92:95], off
	v_max_f32_e32 v88, 0, v88
	v_max_f32_e32 v87, 0, v87
	v_mul_f32_e32 v92, v84, v84
	v_max_f32_e32 v84, 0, v89
	v_mul_f32_e32 v89, v85, v85
	v_max_f32_e32 v85, 0, v90
	v_mul_f32_e32 v90, v86, v86
	v_max_f32_e32 v86, 0, v91
	v_mul_f32_e32 v84, v84, v84
	v_mul_f32_e32 v85, v85, v85
	v_mul_f32_e32 v86, v86, v86
	v_pk_mul_f32 v[76:77], v[76:77], v[154:155] op_sel_hi:[1,0]
	v_mul_f32_e32 v88, v88, v88
	v_mul_f32_e32 v87, v87, v87
	v_cvt_pk_bf16_f32 v84, v88, v84
	v_cvt_pk_bf16_f32 v85, v85, v86
	v_cvt_pk_bf16_f32 v86, v92, v89
	v_pk_mul_f32 v[80:81], v[80:81], v[154:155] op_sel_hi:[1,0]
	v_pk_mul_f32 v[78:79], v[78:79], v[154:155] op_sel_hi:[1,0]
	v_max_f32_e32 v76, 0, v76
	v_cvt_pk_bf16_f32 v87, v90, v87
	global_store_dwordx4 v[100:101], v[84:87], off offset:256
	v_pk_mul_f32 v[82:83], v[82:83], v[154:155] op_sel_hi:[1,0]
	v_max_f32_e32 v77, 0, v77
	v_mul_f32_e32 v86, v76, v76
	v_max_f32_e32 v76, 0, v81
	v_max_f32_e32 v78, 0, v78
	v_mad_i64_i32 v[84:85], s[30:31], v144, s48, v[168:169]
	v_max_f32_e32 v80, 0, v80
	v_mul_f32_e32 v76, v76, v76
	v_mul_f32_e32 v81, v77, v77
	v_max_f32_e32 v77, 0, v82
	v_mul_f32_e32 v82, v78, v78
	v_max_f32_e32 v78, 0, v83
	v_max_f32_e32 v79, 0, v79
	v_pk_mul_f32 v[70:71], v[70:71], v[154:155] op_sel_hi:[1,0]
	v_pk_mul_f32 v[68:69], v[68:69], v[154:155] op_sel_hi:[1,0]
	v_lshl_add_u64 v[84:85], v[84:85], 0, v[150:151]
	v_mul_f32_e32 v80, v80, v80
	v_mul_f32_e32 v77, v77, v77
	v_mul_f32_e32 v78, v78, v78
	v_mul_f32_e32 v79, v79, v79
	v_cvt_pk_bf16_f32 v76, v80, v76
	v_pk_mul_f32 v[74:75], v[74:75], v[154:155] op_sel_hi:[1,0]
	v_pk_mul_f32 v[72:73], v[72:73], v[154:155] op_sel_hi:[1,0]
	v_max_f32_e32 v68, 0, v68
	v_max_f32_e32 v69, 0, v69
	v_max_f32_e32 v70, 0, v70
	v_cvt_pk_bf16_f32 v77, v77, v78
	v_cvt_pk_bf16_f32 v78, v86, v81
	v_cvt_pk_bf16_f32 v79, v82, v79
	global_store_dwordx4 v[84:85], v[76:79], off
	v_max_f32_e32 v72, 0, v72
	v_max_f32_e32 v71, 0, v71
	v_mul_f32_e32 v76, v68, v68
	v_max_f32_e32 v68, 0, v73
	v_mul_f32_e32 v73, v69, v69
	v_max_f32_e32 v69, 0, v74
	v_mul_f32_e32 v74, v70, v70
	v_max_f32_e32 v70, 0, v75
	v_mul_f32_e32 v68, v68, v68
	v_mul_f32_e32 v69, v69, v69
	v_mul_f32_e32 v70, v70, v70
	v_pk_mul_f32 v[60:61], v[60:61], v[152:153] op_sel_hi:[1,0]
	v_mul_f32_e32 v72, v72, v72
	v_mul_f32_e32 v71, v71, v71
	v_cvt_pk_bf16_f32 v68, v72, v68
	v_cvt_pk_bf16_f32 v69, v69, v70
	v_cvt_pk_bf16_f32 v70, v76, v73
	v_pk_mul_f32 v[64:65], v[64:65], v[152:153] op_sel_hi:[1,0]
	v_pk_mul_f32 v[62:63], v[62:63], v[152:153] op_sel_hi:[1,0]
	v_max_f32_e32 v60, 0, v60
	v_cvt_pk_bf16_f32 v71, v74, v71
	global_store_dwordx4 v[84:85], v[68:71], off offset:256
	v_pk_mul_f32 v[66:67], v[66:67], v[152:153] op_sel_hi:[1,0]
	v_max_f32_e32 v61, 0, v61
	v_mul_f32_e32 v70, v60, v60
	v_max_f32_e32 v60, 0, v65
	v_max_f32_e32 v62, 0, v62
	v_mad_i64_i32 v[68:69], s[30:31], v170, s48, v[168:169]
	v_max_f32_e32 v64, 0, v64
	v_mul_f32_e32 v60, v60, v60
	v_mul_f32_e32 v65, v61, v61
	v_max_f32_e32 v61, 0, v66
	v_mul_f32_e32 v66, v62, v62
	v_max_f32_e32 v62, 0, v67
	v_max_f32_e32 v63, 0, v63
	v_pk_mul_f32 v[54:55], v[54:55], v[152:153] op_sel_hi:[1,0]
	v_pk_mul_f32 v[52:53], v[52:53], v[152:153] op_sel_hi:[1,0]
	v_lshl_add_u64 v[68:69], v[68:69], 0, v[150:151]
	v_mul_f32_e32 v64, v64, v64
	v_mul_f32_e32 v61, v61, v61
	v_mul_f32_e32 v62, v62, v62
	v_mul_f32_e32 v63, v63, v63
	v_cvt_pk_bf16_f32 v60, v64, v60
	v_pk_mul_f32 v[58:59], v[58:59], v[152:153] op_sel_hi:[1,0]
	v_pk_mul_f32 v[56:57], v[56:57], v[152:153] op_sel_hi:[1,0]
	v_max_f32_e32 v52, 0, v52
	v_max_f32_e32 v53, 0, v53
	v_max_f32_e32 v54, 0, v54
	v_cvt_pk_bf16_f32 v61, v61, v62
	v_cvt_pk_bf16_f32 v62, v70, v65
	v_cvt_pk_bf16_f32 v63, v66, v63
	global_store_dwordx4 v[68:69], v[60:63], off
	v_max_f32_e32 v56, 0, v56
	v_max_f32_e32 v55, 0, v55
	v_mul_f32_e32 v60, v52, v52
	v_max_f32_e32 v52, 0, v57
	v_mul_f32_e32 v57, v53, v53
	v_max_f32_e32 v53, 0, v58
	v_mul_f32_e32 v58, v54, v54
	v_max_f32_e32 v54, 0, v59
	v_mul_f32_e32 v52, v52, v52
	v_mul_f32_e32 v53, v53, v53
	v_mul_f32_e32 v54, v54, v54
	v_pk_mul_f32 v[44:45], v[44:45], v[162:163] op_sel_hi:[1,0]
	v_mul_f32_e32 v56, v56, v56
	v_mul_f32_e32 v55, v55, v55
	v_cvt_pk_bf16_f32 v52, v56, v52
	v_cvt_pk_bf16_f32 v53, v53, v54
	v_cvt_pk_bf16_f32 v54, v60, v57
	v_pk_mul_f32 v[48:49], v[48:49], v[162:163] op_sel_hi:[1,0]
	v_pk_mul_f32 v[46:47], v[46:47], v[162:163] op_sel_hi:[1,0]
	v_max_f32_e32 v44, 0, v44
	v_cvt_pk_bf16_f32 v55, v58, v55
	global_store_dwordx4 v[68:69], v[52:55], off offset:256
	v_pk_mul_f32 v[50:51], v[50:51], v[162:163] op_sel_hi:[1,0]
	v_max_f32_e32 v45, 0, v45
	v_mul_f32_e32 v54, v44, v44
	v_max_f32_e32 v44, 0, v49
	v_max_f32_e32 v46, 0, v46
	v_mad_i64_i32 v[52:53], s[30:31], v149, s48, v[168:169]
	v_max_f32_e32 v48, 0, v48
	v_mul_f32_e32 v44, v44, v44
	v_mul_f32_e32 v49, v45, v45
	v_max_f32_e32 v45, 0, v50
	v_mul_f32_e32 v50, v46, v46
	v_max_f32_e32 v46, 0, v51
	v_max_f32_e32 v47, 0, v47
	v_pk_mul_f32 v[38:39], v[38:39], v[162:163] op_sel_hi:[1,0]
	v_pk_mul_f32 v[36:37], v[36:37], v[162:163] op_sel_hi:[1,0]
	v_lshl_add_u64 v[52:53], v[52:53], 0, v[150:151]
	v_mul_f32_e32 v48, v48, v48
	v_mul_f32_e32 v45, v45, v45
	v_mul_f32_e32 v46, v46, v46
	v_mul_f32_e32 v47, v47, v47
	v_cvt_pk_bf16_f32 v44, v48, v44
	v_pk_mul_f32 v[42:43], v[42:43], v[162:163] op_sel_hi:[1,0]
	v_pk_mul_f32 v[40:41], v[40:41], v[162:163] op_sel_hi:[1,0]
	v_max_f32_e32 v36, 0, v36
	v_max_f32_e32 v37, 0, v37
	v_max_f32_e32 v38, 0, v38
	v_cvt_pk_bf16_f32 v45, v45, v46
	v_cvt_pk_bf16_f32 v46, v54, v49
	v_cvt_pk_bf16_f32 v47, v50, v47
	global_store_dwordx4 v[52:53], v[44:47], off
	v_max_f32_e32 v40, 0, v40
	v_max_f32_e32 v39, 0, v39
	v_mul_f32_e32 v44, v36, v36
	v_max_f32_e32 v36, 0, v41
	v_mul_f32_e32 v41, v37, v37
	v_max_f32_e32 v37, 0, v42
	v_mul_f32_e32 v42, v38, v38
	v_max_f32_e32 v38, 0, v43
	v_mul_f32_e32 v36, v36, v36
	v_mul_f32_e32 v37, v37, v37
	v_mul_f32_e32 v38, v38, v38
	v_pk_mul_f32 v[28:29], v[28:29], v[166:167] op_sel_hi:[1,0]
	v_mul_f32_e32 v40, v40, v40
	v_mul_f32_e32 v39, v39, v39
	v_cvt_pk_bf16_f32 v36, v40, v36
	v_cvt_pk_bf16_f32 v37, v37, v38
	v_cvt_pk_bf16_f32 v38, v44, v41
	v_pk_mul_f32 v[32:33], v[32:33], v[166:167] op_sel_hi:[1,0]
	v_pk_mul_f32 v[30:31], v[30:31], v[166:167] op_sel_hi:[1,0]
	v_max_f32_e32 v28, 0, v28
	v_cvt_pk_bf16_f32 v39, v42, v39
	global_store_dwordx4 v[52:53], v[36:39], off offset:256
	v_pk_mul_f32 v[34:35], v[34:35], v[166:167] op_sel_hi:[1,0]
	v_max_f32_e32 v29, 0, v29
	v_mul_f32_e32 v38, v28, v28
	v_max_f32_e32 v28, 0, v33
	v_max_f32_e32 v30, 0, v30
	v_mad_i64_i32 v[36:37], s[30:31], v147, s48, v[168:169]
	v_max_f32_e32 v32, 0, v32
	v_mul_f32_e32 v28, v28, v28
	v_mul_f32_e32 v33, v29, v29
	v_max_f32_e32 v29, 0, v34
	v_mul_f32_e32 v34, v30, v30
	v_max_f32_e32 v30, 0, v35
	v_max_f32_e32 v31, 0, v31
	v_pk_mul_f32 v[22:23], v[22:23], v[166:167] op_sel_hi:[1,0]
	v_pk_mul_f32 v[20:21], v[20:21], v[166:167] op_sel_hi:[1,0]
	v_lshl_add_u64 v[36:37], v[36:37], 0, v[150:151]
	v_mul_f32_e32 v32, v32, v32
	v_mul_f32_e32 v29, v29, v29
	v_mul_f32_e32 v30, v30, v30
	v_mul_f32_e32 v31, v31, v31
	v_cvt_pk_bf16_f32 v28, v32, v28
	v_pk_mul_f32 v[26:27], v[26:27], v[166:167] op_sel_hi:[1,0]
	v_pk_mul_f32 v[24:25], v[24:25], v[166:167] op_sel_hi:[1,0]
	v_max_f32_e32 v20, 0, v20
	v_max_f32_e32 v21, 0, v21
	v_max_f32_e32 v22, 0, v22
	v_cvt_pk_bf16_f32 v29, v29, v30
	v_cvt_pk_bf16_f32 v30, v38, v33
	v_cvt_pk_bf16_f32 v31, v34, v31
	global_store_dwordx4 v[36:37], v[28:31], off
	v_max_f32_e32 v24, 0, v24
	v_max_f32_e32 v23, 0, v23
	v_mul_f32_e32 v28, v20, v20
	v_max_f32_e32 v20, 0, v25
	v_mul_f32_e32 v25, v21, v21
	v_max_f32_e32 v21, 0, v26
	v_mul_f32_e32 v26, v22, v22
	v_max_f32_e32 v22, 0, v27
	v_mul_f32_e32 v20, v20, v20
	v_mul_f32_e32 v21, v21, v21
	v_mul_f32_e32 v22, v22, v22
	v_pk_mul_f32 v[12:13], v[12:13], v[164:165] op_sel_hi:[1,0]
	v_mul_f32_e32 v24, v24, v24
	v_mul_f32_e32 v23, v23, v23
	v_cvt_pk_bf16_f32 v20, v24, v20
	v_cvt_pk_bf16_f32 v21, v21, v22
	v_cvt_pk_bf16_f32 v22, v28, v25
	v_pk_mul_f32 v[16:17], v[16:17], v[164:165] op_sel_hi:[1,0]
	v_pk_mul_f32 v[14:15], v[14:15], v[164:165] op_sel_hi:[1,0]
	v_max_f32_e32 v12, 0, v12
	v_cvt_pk_bf16_f32 v23, v26, v23
	global_store_dwordx4 v[36:37], v[20:23], off offset:256
	v_pk_mul_f32 v[18:19], v[18:19], v[164:165] op_sel_hi:[1,0]
	v_max_f32_e32 v13, 0, v13
	v_mul_f32_e32 v22, v12, v12
	v_max_f32_e32 v12, 0, v17
	v_max_f32_e32 v14, 0, v14
	v_mad_i64_i32 v[20:21], s[30:31], v145, s48, v[168:169]
	v_max_f32_e32 v16, 0, v16
	v_mul_f32_e32 v12, v12, v12
	v_mul_f32_e32 v17, v13, v13
	v_max_f32_e32 v13, 0, v18
	v_mul_f32_e32 v18, v14, v14
	v_max_f32_e32 v14, 0, v19
	v_max_f32_e32 v15, 0, v15
	v_pk_mul_f32 v[6:7], v[6:7], v[164:165] op_sel_hi:[1,0]
	v_pk_mul_f32 v[4:5], v[4:5], v[164:165] op_sel_hi:[1,0]
	v_lshl_add_u64 v[20:21], v[20:21], 0, v[150:151]
	v_mul_f32_e32 v16, v16, v16
	v_mul_f32_e32 v13, v13, v13
	v_mul_f32_e32 v14, v14, v14
	v_mul_f32_e32 v15, v15, v15
	v_cvt_pk_bf16_f32 v12, v16, v12
	v_pk_mul_f32 v[10:11], v[10:11], v[164:165] op_sel_hi:[1,0]
	v_pk_mul_f32 v[8:9], v[8:9], v[164:165] op_sel_hi:[1,0]
	v_max_f32_e32 v4, 0, v4
	v_max_f32_e32 v5, 0, v5
	v_max_f32_e32 v6, 0, v6
	v_cvt_pk_bf16_f32 v13, v13, v14
	v_cvt_pk_bf16_f32 v14, v22, v17
	v_cvt_pk_bf16_f32 v15, v18, v15
	global_store_dwordx4 v[20:21], v[12:15], off
	v_max_f32_e32 v7, 0, v7
	v_max_f32_e32 v8, 0, v8
	v_mul_f32_e32 v12, v4, v4
	v_max_f32_e32 v4, 0, v9
	v_mul_f32_e32 v9, v5, v5
	v_max_f32_e32 v5, 0, v10
	v_mul_f32_e32 v10, v6, v6
	v_max_f32_e32 v6, 0, v11
	v_mul_f32_e32 v4, v4, v4
	v_mul_f32_e32 v5, v5, v5
	v_mul_f32_e32 v6, v6, v6
	v_mul_f32_e32 v7, v7, v7
	s_mov_b64 s[30:31], -1
	v_mul_f32_e32 v8, v8, v8
	v_cvt_pk_bf16_f32 v4, v8, v4
	v_cvt_pk_bf16_f32 v5, v5, v6
	v_cvt_pk_bf16_f32 v6, v12, v9
	v_cvt_pk_bf16_f32 v7, v10, v7
	global_store_dwordx4 v[20:21], v[4:7], off offset:256
	s_cbranch_vccnz .LBB0_1129
	s_andn2_b64 vcc, exec, s[12:13]
	s_cbranch_vccnz .LBB0_1128
	s_barrier
	s_branch .LBB0_1128

.LBB0_1167:
	s_add_u32 s0, s36, 0xfff80080
	s_addc_u32 s6, s37, -1
	s_add_i32 s49, 0, 0x10000
	s_cmp_eq_u32 s67, 28
	s_cselect_b32 s35, s43, s6
	s_cselect_b32 s34, s65, s0
	v_add_u32_e32 v156, s49, v157
	s_cselect_b32 s31, s29, s39
	s_cselect_b32 s30, s66, s38
	s_add_i32 s0, 0, 0x14000
	ds_read_b128 v[144:147], v156
	ds_read_b128 v[148:151], v156 offset:1024
	ds_read_b128 v[152:155], v156 offset:2048
	ds_read_b128 v[162:165], v156 offset:3072
	v_add_u32_e32 v156, s0, v157
	ds_read_b128 v[166:169], v156
	ds_read_b128 v[170:173], v156 offset:1024
	ds_read_b128 v[174:177], v156 offset:2048
	ds_read_b128 v[178:181], v156 offset:3072
	v_lshl_add_u64 v[194:195], s[36:37], 0, v[140:141]
	s_add_i32 m0, s25, 0xc000
	ds_read_b128 v[182:185], v161
	ds_read_b128 v[186:189], v161 offset:1024
	ds_read_b128 v[190:193], v161 offset:2048
	ds_read_b128 v[200:203], v161 offset:3072
	ds_read_b128 v[204:207], v161 offset:4096
	ds_read_b128 v[208:211], v161 offset:5120
	ds_read_b128 v[212:215], v161 offset:6144
	ds_read_b128 v[216:219], v161 offset:7168
	global_load_lds_dwordx4 v[194:195], off
	s_add_i32 m0, s25, 0xe000
	v_lshl_add_u64 v[194:195], s[36:37], 0, v[142:143]
	global_load_lds_dwordx4 v[194:195], off
	s_setprio 1
	s_waitcnt vmcnt(8) lgkmcnt(0)
	s_barrier
	v_mfma_f32_16x16x32_bf16 v[128:131], v[144:147], v[182:185], v[128:131]
	v_mfma_f32_16x16x32_bf16 v[124:127], v[152:155], v[182:185], v[124:127]
	v_mfma_f32_16x16x32_bf16 v[112:115], v[144:147], v[190:193], v[112:115]
	v_mfma_f32_16x16x32_bf16 v[108:111], v[152:155], v[190:193], v[108:111]
	v_mfma_f32_16x16x32_bf16 v[96:99], v[144:147], v[204:207], v[96:99]
	v_mfma_f32_16x16x32_bf16 v[92:95], v[152:155], v[204:207], v[92:95]
	v_mfma_f32_16x16x32_bf16 v[80:83], v[144:147], v[212:215], v[80:83]
	v_mfma_f32_16x16x32_bf16 v[76:79], v[152:155], v[212:215], v[76:79]
	v_mfma_f32_16x16x32_bf16 v[128:131], v[148:151], v[186:189], v[128:131]
	v_mfma_f32_16x16x32_bf16 v[124:127], v[162:165], v[186:189], v[124:127]
	v_mfma_f32_16x16x32_bf16 v[112:115], v[148:151], v[200:203], v[112:115]
	v_mfma_f32_16x16x32_bf16 v[108:111], v[162:165], v[200:203], v[108:111]
	v_mfma_f32_16x16x32_bf16 v[96:99], v[148:151], v[208:211], v[96:99]
	v_mfma_f32_16x16x32_bf16 v[92:95], v[162:165], v[208:211], v[92:95]
	v_mfma_f32_16x16x32_bf16 v[80:83], v[148:151], v[216:219], v[80:83]
	v_mfma_f32_16x16x32_bf16 v[76:79], v[162:165], v[216:219], v[76:79]
	s_setprio 0
	s_setprio 1
	v_mfma_f32_16x16x32_bf16 v[120:123], v[166:169], v[182:185], v[120:123]
	v_mfma_f32_16x16x32_bf16 v[116:119], v[174:177], v[182:185], v[116:119]
	v_mfma_f32_16x16x32_bf16 v[104:107], v[166:169], v[190:193], v[104:107]
	v_mfma_f32_16x16x32_bf16 v[100:103], v[174:177], v[190:193], v[100:103]
	v_mfma_f32_16x16x32_bf16 v[88:91], v[166:169], v[204:207], v[88:91]
	v_mfma_f32_16x16x32_bf16 v[84:87], v[174:177], v[204:207], v[84:87]
	v_mfma_f32_16x16x32_bf16 v[72:75], v[166:169], v[212:215], v[72:75]
	v_mfma_f32_16x16x32_bf16 v[68:71], v[174:177], v[212:215], v[68:71]
	v_mfma_f32_16x16x32_bf16 v[120:123], v[170:173], v[186:189], v[120:123]
	v_mfma_f32_16x16x32_bf16 v[116:119], v[178:181], v[186:189], v[116:119]
	v_mfma_f32_16x16x32_bf16 v[104:107], v[170:173], v[200:203], v[104:107]
	v_mfma_f32_16x16x32_bf16 v[100:103], v[178:181], v[200:203], v[100:103]
	v_mfma_f32_16x16x32_bf16 v[88:91], v[170:173], v[208:211], v[88:91]
	v_mfma_f32_16x16x32_bf16 v[84:87], v[178:181], v[208:211], v[84:87]
	v_mfma_f32_16x16x32_bf16 v[72:75], v[170:173], v[216:219], v[72:75]
	v_mfma_f32_16x16x32_bf16 v[68:71], v[178:181], v[216:219], v[68:71]
	s_barrier
	s_setprio 0
	s_add_i32 s6, s49, s1
	v_lshl_add_u64 v[194:195], s[30:31], 0, v[136:137]
	s_mov_b32 m0, s6
	ds_read_b128 v[182:185], v161 offset:16384
	ds_read_b128 v[186:189], v161 offset:17408
	ds_read_b128 v[190:193], v161 offset:18432
	ds_read_b128 v[200:203], v161 offset:19456
	ds_read_b128 v[204:207], v161 offset:20480
	ds_read_b128 v[208:211], v161 offset:21504
	ds_read_b128 v[212:215], v161 offset:22528
	ds_read_b128 v[216:219], v161 offset:23552
	global_load_lds_dwordx4 v[194:195], off
	s_add_i32 m0, s6, 0x2000
	s_add_u32 s68, s30, 0x80000
	v_lshl_add_u64 v[198:199], s[30:31], 0, v[132:133]
	s_addc_u32 s69, s31, 0
	s_add_i32 s0, s0, s1
	global_load_lds_dwordx4 v[198:199], off
	v_lshl_add_u64 v[220:221], s[68:69], 0, v[136:137]
	s_mov_b32 m0, s0
	global_load_lds_dwordx4 v[220:221], off
	s_add_i32 m0, s0, 0x2000
	v_lshl_add_u64 v[220:221], s[68:69], 0, v[132:133]
	global_load_lds_dwordx4 v[220:221], off
	s_mov_b32 m0, s25
	v_lshl_add_u64 v[220:221], s[34:35], 0, v[138:139]
	global_load_lds_dwordx4 v[220:221], off
	s_mov_b32 m0, s33
	v_lshl_add_u64 v[222:223], s[34:35], 0, v[134:135]
	global_load_lds_dwordx4 v[222:223], off
	s_setprio 1
	s_waitcnt vmcnt(8) lgkmcnt(0)
	s_barrier
	v_mfma_f32_16x16x32_bf16 v[64:67], v[144:147], v[182:185], v[64:67]
	v_mfma_f32_16x16x32_bf16 v[60:63], v[152:155], v[182:185], v[60:63]
	v_mfma_f32_16x16x32_bf16 v[48:51], v[144:147], v[190:193], v[48:51]
	v_mfma_f32_16x16x32_bf16 v[44:47], v[152:155], v[190:193], v[44:47]
	v_mfma_f32_16x16x32_bf16 v[32:35], v[144:147], v[204:207], v[32:35]
	v_mfma_f32_16x16x32_bf16 v[28:31], v[152:155], v[204:207], v[28:31]
	v_mfma_f32_16x16x32_bf16 v[16:19], v[144:147], v[212:215], v[16:19]
	v_mfma_f32_16x16x32_bf16 v[12:15], v[152:155], v[212:215], v[12:15]
	v_mfma_f32_16x16x32_bf16 v[64:67], v[148:151], v[186:189], v[64:67]
	v_mfma_f32_16x16x32_bf16 v[60:63], v[162:165], v[186:189], v[60:63]
	v_mfma_f32_16x16x32_bf16 v[48:51], v[148:151], v[200:203], v[48:51]
	v_mfma_f32_16x16x32_bf16 v[44:47], v[162:165], v[200:203], v[44:47]
	v_mfma_f32_16x16x32_bf16 v[32:35], v[148:151], v[208:211], v[32:35]
	v_mfma_f32_16x16x32_bf16 v[28:31], v[162:165], v[208:211], v[28:31]
	v_mfma_f32_16x16x32_bf16 v[16:19], v[148:151], v[216:219], v[16:19]
	v_mfma_f32_16x16x32_bf16 v[12:15], v[162:165], v[216:219], v[12:15]
	s_setprio 0
	s_setprio 1
	v_mfma_f32_16x16x32_bf16 v[56:59], v[166:169], v[182:185], v[56:59]
	v_mfma_f32_16x16x32_bf16 v[52:55], v[174:177], v[182:185], v[52:55]
	v_mfma_f32_16x16x32_bf16 v[40:43], v[166:169], v[190:193], v[40:43]
	v_mfma_f32_16x16x32_bf16 v[36:39], v[174:177], v[190:193], v[36:39]
	v_mfma_f32_16x16x32_bf16 v[24:27], v[166:169], v[204:207], v[24:27]
	v_mfma_f32_16x16x32_bf16 v[20:23], v[174:177], v[204:207], v[20:23]
	v_mfma_f32_16x16x32_bf16 v[8:11], v[166:169], v[212:215], v[8:11]
	v_mfma_f32_16x16x32_bf16 v[4:7], v[174:177], v[212:215], v[4:7]
	v_mfma_f32_16x16x32_bf16 v[56:59], v[170:173], v[186:189], v[56:59]
	v_mfma_f32_16x16x32_bf16 v[52:55], v[178:181], v[186:189], v[52:55]
	v_mfma_f32_16x16x32_bf16 v[40:43], v[170:173], v[200:203], v[40:43]
	v_mfma_f32_16x16x32_bf16 v[36:39], v[178:181], v[200:203], v[36:39]
	v_mfma_f32_16x16x32_bf16 v[24:27], v[170:173], v[208:211], v[24:27]
	v_mfma_f32_16x16x32_bf16 v[20:23], v[178:181], v[208:211], v[20:23]
	v_mfma_f32_16x16x32_bf16 v[8:11], v[170:173], v[216:219], v[8:11]
	v_mfma_f32_16x16x32_bf16 v[4:7], v[178:181], v[216:219], v[4:7]
	s_barrier
	s_setprio 0
	s_add_i32 s0, 0, 0x18000
	v_add_u32_e32 v156, s0, v157
	s_add_i32 s6, 0, 0x1c000
	ds_read_b128 v[144:147], v156
	ds_read_b128 v[148:151], v156 offset:1024
	ds_read_b128 v[152:155], v156 offset:2048
	ds_read_b128 v[162:165], v156 offset:3072
	v_add_u32_e32 v156, s6, v157
	ds_read_b128 v[166:169], v156
	ds_read_b128 v[170:173], v156 offset:1024
	ds_read_b128 v[174:177], v156 offset:2048
	ds_read_b128 v[178:181], v156 offset:3072
	s_add_u32 s34, s34, 0x80000
	s_addc_u32 s35, s35, 0
	s_mov_b32 m0, s40
	v_lshl_add_u64 v[224:225], s[34:35], 0, v[138:139]
	ds_read_b128 v[182:185], v161 offset:32768
	ds_read_b128 v[186:189], v161 offset:33792
	ds_read_b128 v[190:193], v161 offset:34816
	ds_read_b128 v[200:203], v161 offset:35840
	ds_read_b128 v[204:207], v161 offset:36864
	ds_read_b128 v[208:211], v161 offset:37888
	ds_read_b128 v[212:215], v161 offset:38912
	ds_read_b128 v[216:219], v161 offset:39936
	global_load_lds_dwordx4 v[224:225], off
	s_mov_b32 m0, s50
	v_lshl_add_u64 v[224:225], s[34:35], 0, v[134:135]
	global_load_lds_dwordx4 v[224:225], off
	s_setprio 1
	s_waitcnt vmcnt(8) lgkmcnt(0)
	s_barrier
	v_mfma_f32_16x16x32_bf16 v[128:131], v[144:147], v[182:185], v[128:131]
	v_mfma_f32_16x16x32_bf16 v[124:127], v[152:155], v[182:185], v[124:127]
	v_mfma_f32_16x16x32_bf16 v[112:115], v[144:147], v[190:193], v[112:115]
	v_mfma_f32_16x16x32_bf16 v[108:111], v[152:155], v[190:193], v[108:111]
	v_mfma_f32_16x16x32_bf16 v[96:99], v[144:147], v[204:207], v[96:99]
	v_mfma_f32_16x16x32_bf16 v[92:95], v[152:155], v[204:207], v[92:95]
	v_mfma_f32_16x16x32_bf16 v[80:83], v[144:147], v[212:215], v[80:83]
	v_mfma_f32_16x16x32_bf16 v[76:79], v[152:155], v[212:215], v[76:79]
	v_mfma_f32_16x16x32_bf16 v[128:131], v[148:151], v[186:189], v[128:131]
	v_mfma_f32_16x16x32_bf16 v[124:127], v[162:165], v[186:189], v[124:127]
	v_mfma_f32_16x16x32_bf16 v[112:115], v[148:151], v[200:203], v[112:115]
	v_mfma_f32_16x16x32_bf16 v[108:111], v[162:165], v[200:203], v[108:111]
	v_mfma_f32_16x16x32_bf16 v[96:99], v[148:151], v[208:211], v[96:99]
	v_mfma_f32_16x16x32_bf16 v[92:95], v[162:165], v[208:211], v[92:95]
	v_mfma_f32_16x16x32_bf16 v[80:83], v[148:151], v[216:219], v[80:83]
	v_mfma_f32_16x16x32_bf16 v[76:79], v[162:165], v[216:219], v[76:79]
	s_setprio 0
	s_setprio 1
	v_mfma_f32_16x16x32_bf16 v[120:123], v[166:169], v[182:185], v[120:123]
	v_mfma_f32_16x16x32_bf16 v[116:119], v[174:177], v[182:185], v[116:119]
	v_mfma_f32_16x16x32_bf16 v[104:107], v[166:169], v[190:193], v[104:107]
	v_mfma_f32_16x16x32_bf16 v[100:103], v[174:177], v[190:193], v[100:103]
	v_mfma_f32_16x16x32_bf16 v[88:91], v[166:169], v[204:207], v[88:91]
	v_mfma_f32_16x16x32_bf16 v[84:87], v[174:177], v[204:207], v[84:87]
	v_mfma_f32_16x16x32_bf16 v[72:75], v[166:169], v[212:215], v[72:75]
	v_mfma_f32_16x16x32_bf16 v[68:71], v[174:177], v[212:215], v[68:71]
	v_mfma_f32_16x16x32_bf16 v[120:123], v[170:173], v[186:189], v[120:123]
	v_mfma_f32_16x16x32_bf16 v[116:119], v[178:181], v[186:189], v[116:119]
	v_mfma_f32_16x16x32_bf16 v[104:107], v[170:173], v[200:203], v[104:107]
	v_mfma_f32_16x16x32_bf16 v[100:103], v[178:181], v[200:203], v[100:103]
	v_mfma_f32_16x16x32_bf16 v[88:91], v[170:173], v[208:211], v[88:91]
	v_mfma_f32_16x16x32_bf16 v[84:87], v[178:181], v[208:211], v[84:87]
	v_mfma_f32_16x16x32_bf16 v[72:75], v[170:173], v[216:219], v[72:75]
	v_mfma_f32_16x16x32_bf16 v[68:71], v[178:181], v[216:219], v[68:71]
	s_barrier
	s_setprio 0
	s_add_i32 s0, s0, s1
	v_lshl_add_u64 v[194:195], v[194:195], 0, s[90:91]
	s_mov_b32 m0, s0
	ds_read_b128 v[182:185], v161 offset:49152
	ds_read_b128 v[186:189], v161 offset:50176
	ds_read_b128 v[190:193], v161 offset:51200
	ds_read_b128 v[200:203], v161 offset:52224
	ds_read_b128 v[204:207], v161 offset:53248
	ds_read_b128 v[208:211], v161 offset:54272
	ds_read_b128 v[212:215], v161 offset:55296
	ds_read_b128 v[216:219], v161 offset:56320
	global_load_lds_dwordx4 v[194:195], off
	s_add_i32 m0, s0, 0x2000
	s_add_u32 s30, s30, 0x80080
	v_lshl_add_u64 v[194:195], v[198:199], 0, s[90:91]
	s_addc_u32 s31, s31, 0
	s_add_i32 s0, s6, s1
	global_load_lds_dwordx4 v[194:195], off
	s_mov_b32 m0, s0
	v_lshl_add_u64 v[194:195], s[30:31], 0, v[136:137]
	global_load_lds_dwordx4 v[194:195], off
	s_add_i32 m0, s0, 0x2000
	v_lshl_add_u64 v[194:195], s[30:31], 0, v[132:133]
	global_load_lds_dwordx4 v[194:195], off
	s_mov_b32 m0, s51
	v_lshl_add_u64 v[194:195], v[220:221], 0, s[90:91]
	global_load_lds_dwordx4 v[194:195], off
	s_mov_b32 m0, s55
	v_lshl_add_u64 v[194:195], v[222:223], 0, s[90:91]
	global_load_lds_dwordx4 v[194:195], off
	s_setprio 1
	s_waitcnt vmcnt(8) lgkmcnt(0)
	s_barrier
	v_mfma_f32_16x16x32_bf16 v[64:67], v[144:147], v[182:185], v[64:67]
	v_mfma_f32_16x16x32_bf16 v[60:63], v[152:155], v[182:185], v[60:63]
	v_mfma_f32_16x16x32_bf16 v[48:51], v[144:147], v[190:193], v[48:51]
	v_mfma_f32_16x16x32_bf16 v[44:47], v[152:155], v[190:193], v[44:47]
	v_mfma_f32_16x16x32_bf16 v[32:35], v[144:147], v[204:207], v[32:35]
	v_mfma_f32_16x16x32_bf16 v[28:31], v[152:155], v[204:207], v[28:31]
	v_mfma_f32_16x16x32_bf16 v[16:19], v[144:147], v[212:215], v[16:19]
	v_mfma_f32_16x16x32_bf16 v[12:15], v[152:155], v[212:215], v[12:15]
	v_mfma_f32_16x16x32_bf16 v[64:67], v[148:151], v[186:189], v[64:67]
	v_mfma_f32_16x16x32_bf16 v[60:63], v[162:165], v[186:189], v[60:63]
	v_mfma_f32_16x16x32_bf16 v[48:51], v[148:151], v[200:203], v[48:51]
	v_mfma_f32_16x16x32_bf16 v[44:47], v[162:165], v[200:203], v[44:47]
	v_mfma_f32_16x16x32_bf16 v[32:35], v[148:151], v[208:211], v[32:35]
	v_mfma_f32_16x16x32_bf16 v[28:31], v[162:165], v[208:211], v[28:31]
	v_mfma_f32_16x16x32_bf16 v[16:19], v[148:151], v[216:219], v[16:19]
	v_mfma_f32_16x16x32_bf16 v[12:15], v[162:165], v[216:219], v[12:15]
	s_setprio 0
	s_setprio 1
	v_mfma_f32_16x16x32_bf16 v[56:59], v[166:169], v[182:185], v[56:59]
	v_mfma_f32_16x16x32_bf16 v[52:55], v[174:177], v[182:185], v[52:55]
	v_mfma_f32_16x16x32_bf16 v[40:43], v[166:169], v[190:193], v[40:43]
	v_mfma_f32_16x16x32_bf16 v[36:39], v[174:177], v[190:193], v[36:39]
	v_mfma_f32_16x16x32_bf16 v[24:27], v[166:169], v[204:207], v[24:27]
	v_mfma_f32_16x16x32_bf16 v[20:23], v[174:177], v[204:207], v[20:23]
	v_mfma_f32_16x16x32_bf16 v[8:11], v[166:169], v[212:215], v[8:11]
	v_mfma_f32_16x16x32_bf16 v[4:7], v[174:177], v[212:215], v[4:7]
	v_mfma_f32_16x16x32_bf16 v[56:59], v[170:173], v[186:189], v[56:59]
	v_mfma_f32_16x16x32_bf16 v[52:55], v[178:181], v[186:189], v[52:55]
	v_mfma_f32_16x16x32_bf16 v[40:43], v[170:173], v[200:203], v[40:43]
	v_mfma_f32_16x16x32_bf16 v[36:39], v[178:181], v[200:203], v[36:39]
	v_mfma_f32_16x16x32_bf16 v[24:27], v[170:173], v[208:211], v[24:27]
	v_mfma_f32_16x16x32_bf16 v[20:23], v[178:181], v[208:211], v[20:23]
	v_mfma_f32_16x16x32_bf16 v[8:11], v[170:173], v[216:219], v[8:11]
	v_mfma_f32_16x16x32_bf16 v[4:7], v[178:181], v[216:219], v[4:7]
	s_barrier
	s_setprio 0
	s_add_i32 s67, s67, 2
	s_add_u32 s36, s36, 0x100
	s_addc_u32 s37, s37, 0
	s_add_u32 s38, s38, 0x100
	s_addc_u32 s39, s39, 0
	s_cmp_gt_u32 s67, 29
	s_cbranch_scc0 .LBB0_1167
	s_and_b64 vcc, exec, s[20:21]
	s_mov_b32 s100, 0
	s_cbranch_vccz .LBB0_1170
	s_mov_b32 s100, 1
.LBB0_1170:
	v_lshl_add_u32 v150, s64, 8, v3
	v_ashrrev_i32_e32 v151, 31, v150
	v_lshl_add_u64 v[164:165], v[150:151], 3, s[16:17]
	global_load_dwordx2 v[168:169], v[164:165], off
	v_or_b32_e32 v148, 16, v150
	v_ashrrev_i32_e32 v149, 31, v148
	v_lshl_add_u64 v[144:145], v[148:149], 3, s[16:17]
	global_load_dwordx2 v[172:173], v[144:145], off
	v_or_b32_e32 v146, 32, v150
	v_ashrrev_i32_e32 v147, 31, v146
	v_lshl_add_u64 v[144:145], v[146:147], 3, s[16:17]
	global_load_dwordx2 v[174:175], v[144:145], off
	global_load_dwordx2 v[162:163], v[164:165], off offset:1152
	v_or_b32_e32 v144, 48, v150
	v_ashrrev_i32_e32 v145, 31, v144
	v_lshl_add_u64 v[152:153], v[144:145], 3, s[16:17]
	global_load_dwordx2 v[154:155], v[152:153], off
	global_load_dwordx2 v[166:167], v[164:165], off offset:1280
	v_mov_b32_e32 v177, v2
	global_load_dwordx2 v[152:153], v[164:165], off offset:1024
	s_min_u32 s29, s72, 32
	global_load_dwordx2 v[164:165], v[164:165], off offset:1408
	s_sub_i32 s30, 32, s29
	v_add_u32_e32 v170, 0x80, v150
	v_add_u32_e32 v149, 0x90, v150
	v_add_u32_e32 v147, 0xa0, v150
	v_add_u32_e32 v145, 0xb0, v150
	s_andn2_b64 vcc, exec, s[22:23]
	s_cmp_eq_u32 s100, 0
	s_cbranch_scc1 .Lx_ab_6
	s_barrier
.Lx_ab_6:
	s_waitcnt vmcnt(0)
	v_mov_b32_e32 v176, v169
	v_lshlrev_b64 v[176:177], s29, v[176:177]
	v_min_u32_e32 v151, 1, v176
	v_or_b32_e32 v151, v177, v151
	v_cvt_f32_u32_e32 v151, v151
	v_cvt_f32_u32_e32 v156, v168
	v_mov_b32_e32 v168, v173
	v_mov_b32_e32 v169, v2
	v_ldexp_f32 v151, v151, s30
	v_mul_f32_e32 v151, 0x43800000, v151
	v_fmac_f32_e32 v151, 0x33800000, v156
	v_fmamk_f32 v151, v151, 0x3a000000, v1
	v_lshlrev_b64 v[168:169], s29, v[168:169]
	v_rsq_f32_e32 v160, v151
	v_min_u32_e32 v151, 1, v168
	v_or_b32_e32 v151, v169, v151
	v_cvt_f32_u32_e32 v151, v151
	v_cvt_f32_u32_e32 v156, v172
	v_mov_b32_e32 v168, v175
	v_mov_b32_e32 v169, v2
	v_ldexp_f32 v151, v151, s30
	v_mul_f32_e32 v151, 0x43800000, v151
	v_fmac_f32_e32 v151, 0x33800000, v156
	v_fmamk_f32 v151, v151, 0x3a000000, v1
	v_lshlrev_b64 v[168:169], s29, v[168:169]
	v_rsq_f32_e32 v158, v151
	v_min_u32_e32 v151, 1, v168
	v_or_b32_e32 v151, v169, v151
	v_cvt_f32_u32_e32 v151, v151
	v_cvt_f32_u32_e32 v156, v174
	v_mov_b32_e32 v168, v155
	v_mov_b32_e32 v169, v2
	v_ldexp_f32 v151, v151, s30
	v_mul_f32_e32 v151, 0x43800000, v151
	v_fmac_f32_e32 v151, 0x33800000, v156
	v_fmamk_f32 v151, v151, 0x3a000000, v1
	v_lshlrev_b64 v[168:169], s29, v[168:169]
	v_rsq_f32_e32 v156, v151
	v_min_u32_e32 v151, 1, v168
	v_or_b32_e32 v151, v169, v151
	v_cvt_f32_u32_e32 v151, v151
	v_cvt_f32_u32_e32 v154, v154
	v_mov_b32_e32 v168, v153
	v_mov_b32_e32 v169, v2
	v_ldexp_f32 v151, v151, s30
	v_mul_f32_e32 v151, 0x43800000, v151
	v_fmac_f32_e32 v151, 0x33800000, v154
	v_fmamk_f32 v151, v151, 0x3a000000, v1
	v_lshlrev_b64 v[168:169], s29, v[168:169]
	v_rsq_f32_e32 v154, v151
	v_min_u32_e32 v151, 1, v168
	v_or_b32_e32 v151, v169, v151
	v_cvt_f32_u32_e32 v151, v151
	v_cvt_f32_u32_e32 v152, v152
	v_mov_b32_e32 v168, v163
	v_mov_b32_e32 v169, v2
	v_ldexp_f32 v151, v151, s30
	v_mul_f32_e32 v151, 0x43800000, v151
	v_fmac_f32_e32 v151, 0x33800000, v152
	v_fmamk_f32 v151, v151, 0x3a000000, v1
	v_lshlrev_b64 v[168:169], s29, v[168:169]
	v_rsq_f32_e32 v152, v151
	v_min_u32_e32 v151, 1, v168
	v_or_b32_e32 v151, v169, v151
	v_cvt_f32_u32_e32 v151, v151
	v_cvt_f32_u32_e32 v153, v162
	v_mov_b32_e32 v168, v167
	v_mov_b32_e32 v169, v2
	v_ldexp_f32 v151, v151, s30
	v_mul_f32_e32 v151, 0x43800000, v151
	v_fmac_f32_e32 v151, 0x33800000, v153
	v_fmamk_f32 v151, v151, 0x3a000000, v1
	v_lshlrev_b64 v[168:169], s29, v[168:169]
	v_rsq_f32_e32 v162, v151
	v_min_u32_e32 v151, 1, v168
	v_or_b32_e32 v151, v169, v151
	v_cvt_f32_u32_e32 v151, v151
	v_cvt_f32_u32_e32 v153, v166
	v_mov_b32_e32 v168, v165
	v_mov_b32_e32 v169, v2
	v_ldexp_f32 v151, v151, s30
	v_mul_f32_e32 v151, 0x43800000, v151
	v_fmac_f32_e32 v151, 0x33800000, v153
	v_fmamk_f32 v151, v151, 0x3a000000, v1
	v_lshlrev_b64 v[168:169], s29, v[168:169]
	v_rsq_f32_e32 v166, v151
	v_min_u32_e32 v151, 1, v168
	v_or_b32_e32 v151, v169, v151
	v_cvt_f32_u32_e32 v151, v151
	v_cvt_f32_u32_e32 v153, v164
	v_pk_mul_f32 v[124:125], v[124:125], v[160:161] op_sel_hi:[1,0]
	v_lshl_or_b32 v172, s63, 8, v159
	v_ldexp_f32 v151, v151, s30
	v_mul_f32_e32 v151, 0x43800000, v151
	v_fmac_f32_e32 v151, 0x33800000, v153
	v_pk_mul_f32 v[128:129], v[128:129], v[160:161] op_sel_hi:[1,0]
	v_pk_mul_f32 v[126:127], v[126:127], v[160:161] op_sel_hi:[1,0]
	v_max_f32_e32 v124, 0, v124
	v_fmamk_f32 v151, v151, 0x3a000000, v1
	v_ashrrev_i32_e32 v173, 31, v172
	v_mov_b64_e32 v[168:169], s[14:15]
	v_pk_mul_f32 v[130:131], v[130:131], v[160:161] op_sel_hi:[1,0]
	v_mul_f32_e32 v153, v124, v124
	v_max_f32_e32 v124, 0, v129
	v_max_f32_e32 v125, 0, v125
	v_max_f32_e32 v126, 0, v126
	v_rsq_f32_e32 v164, v151
	v_mad_i64_i32 v[174:175], s[30:31], v150, s48, v[168:169]
	v_lshlrev_b64 v[150:151], 1, v[172:173]
	v_max_f32_e32 v128, 0, v128
	v_mul_f32_e32 v124, v124, v124
	v_mul_f32_e32 v129, v125, v125
	v_max_f32_e32 v125, 0, v130
	v_mul_f32_e32 v130, v126, v126
	v_max_f32_e32 v126, 0, v131
	v_max_f32_e32 v127, 0, v127
	v_pk_mul_f32 v[118:119], v[118:119], v[160:161] op_sel_hi:[1,0]
	v_pk_mul_f32 v[116:117], v[116:117], v[160:161] op_sel_hi:[1,0]
	v_lshl_add_u64 v[172:173], v[174:175], 0, v[150:151]
	v_mul_f32_e32 v128, v128, v128
	v_mul_f32_e32 v125, v125, v125
	v_mul_f32_e32 v126, v126, v126
	v_mul_f32_e32 v127, v127, v127
	v_cvt_pk_bf16_f32 v124, v128, v124
	v_pk_mul_f32 v[122:123], v[122:123], v[160:161] op_sel_hi:[1,0]
	v_pk_mul_f32 v[120:121], v[120:121], v[160:161] op_sel_hi:[1,0]
	v_max_f32_e32 v116, 0, v116
	v_max_f32_e32 v117, 0, v117
	v_max_f32_e32 v118, 0, v118
	v_cvt_pk_bf16_f32 v125, v125, v126
	v_cvt_pk_bf16_f32 v126, v153, v129
	v_cvt_pk_bf16_f32 v127, v130, v127
	global_store_dwordx4 v[172:173], v[124:127], off
	v_max_f32_e32 v120, 0, v120
	v_max_f32_e32 v119, 0, v119
	v_mul_f32_e32 v124, v116, v116
	v_max_f32_e32 v116, 0, v121
	v_mul_f32_e32 v121, v117, v117
	v_max_f32_e32 v117, 0, v122
	v_mul_f32_e32 v122, v118, v118
	v_max_f32_e32 v118, 0, v123
	v_mul_f32_e32 v116, v116, v116
	v_mul_f32_e32 v117, v117, v117
	v_mul_f32_e32 v118, v118, v118
	v_pk_mul_f32 v[108:109], v[108:109], v[158:159] op_sel_hi:[1,0]
	v_mul_f32_e32 v120, v120, v120
	v_mul_f32_e32 v119, v119, v119
	v_cvt_pk_bf16_f32 v116, v120, v116
	v_cvt_pk_bf16_f32 v117, v117, v118
	v_cvt_pk_bf16_f32 v118, v124, v121
	v_pk_mul_f32 v[112:113], v[112:113], v[158:159] op_sel_hi:[1,0]
	v_pk_mul_f32 v[110:111], v[110:111], v[158:159] op_sel_hi:[1,0]
	v_max_f32_e32 v108, 0, v108
	v_cvt_pk_bf16_f32 v119, v122, v119
	global_store_dwordx4 v[172:173], v[116:119], off offset:256
	v_pk_mul_f32 v[114:115], v[114:115], v[158:159] op_sel_hi:[1,0]
	v_max_f32_e32 v109, 0, v109
	v_mul_f32_e32 v118, v108, v108
	v_max_f32_e32 v108, 0, v113
	v_max_f32_e32 v110, 0, v110
	v_mad_i64_i32 v[116:117], s[30:31], v148, s48, v[168:169]
	v_max_f32_e32 v112, 0, v112
	v_mul_f32_e32 v108, v108, v108
	v_mul_f32_e32 v113, v109, v109
	v_max_f32_e32 v109, 0, v114
	v_mul_f32_e32 v114, v110, v110
	v_max_f32_e32 v110, 0, v115
	v_max_f32_e32 v111, 0, v111
	v_pk_mul_f32 v[102:103], v[102:103], v[158:159] op_sel_hi:[1,0]
	v_pk_mul_f32 v[100:101], v[100:101], v[158:159] op_sel_hi:[1,0]
	v_lshl_add_u64 v[116:117], v[116:117], 0, v[150:151]
	v_mul_f32_e32 v112, v112, v112
	v_mul_f32_e32 v109, v109, v109
	v_mul_f32_e32 v110, v110, v110
	v_mul_f32_e32 v111, v111, v111
	v_cvt_pk_bf16_f32 v108, v112, v108
	v_pk_mul_f32 v[106:107], v[106:107], v[158:159] op_sel_hi:[1,0]
	v_pk_mul_f32 v[104:105], v[104:105], v[158:159] op_sel_hi:[1,0]
	v_max_f32_e32 v100, 0, v100
	v_max_f32_e32 v101, 0, v101
	v_max_f32_e32 v102, 0, v102
	v_cvt_pk_bf16_f32 v109, v109, v110
	v_cvt_pk_bf16_f32 v110, v118, v113
	v_cvt_pk_bf16_f32 v111, v114, v111
	global_store_dwordx4 v[116:117], v[108:111], off
	v_max_f32_e32 v104, 0, v104
	v_max_f32_e32 v103, 0, v103
	v_mul_f32_e32 v108, v100, v100
	v_max_f32_e32 v100, 0, v105
	v_mul_f32_e32 v105, v101, v101
	v_max_f32_e32 v101, 0, v106
	v_mul_f32_e32 v106, v102, v102
	v_max_f32_e32 v102, 0, v107
	v_mul_f32_e32 v100, v100, v100
	v_mul_f32_e32 v101, v101, v101
	v_mul_f32_e32 v102, v102, v102
	v_pk_mul_f32 v[92:93], v[92:93], v[156:157] op_sel_hi:[1,0]
	v_mul_f32_e32 v104, v104, v104
	v_mul_f32_e32 v103, v103, v103
	v_cvt_pk_bf16_f32 v100, v104, v100
	v_cvt_pk_bf16_f32 v101, v101, v102
	v_cvt_pk_bf16_f32 v102, v108, v105
	v_pk_mul_f32 v[96:97], v[96:97], v[156:157] op_sel_hi:[1,0]
	v_pk_mul_f32 v[94:95], v[94:95], v[156:157] op_sel_hi:[1,0]
	v_max_f32_e32 v92, 0, v92
	v_cvt_pk_bf16_f32 v103, v106, v103
	global_store_dwordx4 v[116:117], v[100:103], off offset:256
	v_pk_mul_f32 v[98:99], v[98:99], v[156:157] op_sel_hi:[1,0]
	v_max_f32_e32 v93, 0, v93
	v_mul_f32_e32 v102, v92, v92
	v_max_f32_e32 v92, 0, v97
	v_max_f32_e32 v94, 0, v94
	v_mad_i64_i32 v[100:101], s[30:31], v146, s48, v[168:169]
	v_max_f32_e32 v96, 0, v96
	v_mul_f32_e32 v92, v92, v92
	v_mul_f32_e32 v97, v93, v93
	v_max_f32_e32 v93, 0, v98
	v_mul_f32_e32 v98, v94, v94
	v_max_f32_e32 v94, 0, v99
	v_max_f32_e32 v95, 0, v95
	v_pk_mul_f32 v[86:87], v[86:87], v[156:157] op_sel_hi:[1,0]
	v_pk_mul_f32 v[84:85], v[84:85], v[156:157] op_sel_hi:[1,0]
	v_lshl_add_u64 v[100:101], v[100:101], 0, v[150:151]
	v_mul_f32_e32 v96, v96, v96
	v_mul_f32_e32 v93, v93, v93
	v_mul_f32_e32 v94, v94, v94
	v_mul_f32_e32 v95, v95, v95
	v_cvt_pk_bf16_f32 v92, v96, v92
	v_pk_mul_f32 v[90:91], v[90:91], v[156:157] op_sel_hi:[1,0]
	v_pk_mul_f32 v[88:89], v[88:89], v[156:157] op_sel_hi:[1,0]
	v_max_f32_e32 v84, 0, v84
	v_max_f32_e32 v85, 0, v85
	v_max_f32_e32 v86, 0, v86
	v_cvt_pk_bf16_f32 v93, v93, v94
	v_cvt_pk_bf16_f32 v94, v102, v97
	v_cvt_pk_bf16_f32 v95, v98, v95
	global_store_dwordx4 v[100:101], v[92:95], off
	v_max_f32_e32 v88, 0, v88
	v_max_f32_e32 v87, 0, v87
	v_mul_f32_e32 v92, v84, v84
	v_max_f32_e32 v84, 0, v89
	v_mul_f32_e32 v89, v85, v85
	v_max_f32_e32 v85, 0, v90
	v_mul_f32_e32 v90, v86, v86
	v_max_f32_e32 v86, 0, v91
	v_mul_f32_e32 v84, v84, v84
	v_mul_f32_e32 v85, v85, v85
	v_mul_f32_e32 v86, v86, v86
	v_pk_mul_f32 v[76:77], v[76:77], v[154:155] op_sel_hi:[1,0]
	v_mul_f32_e32 v88, v88, v88
	v_mul_f32_e32 v87, v87, v87
	v_cvt_pk_bf16_f32 v84, v88, v84
	v_cvt_pk_bf16_f32 v85, v85, v86
	v_cvt_pk_bf16_f32 v86, v92, v89
	v_pk_mul_f32 v[80:81], v[80:81], v[154:155] op_sel_hi:[1,0]
	v_pk_mul_f32 v[78:79], v[78:79], v[154:155] op_sel_hi:[1,0]
	v_max_f32_e32 v76, 0, v76
	v_cvt_pk_bf16_f32 v87, v90, v87
	global_store_dwordx4 v[100:101], v[84:87], off offset:256
	v_pk_mul_f32 v[82:83], v[82:83], v[154:155] op_sel_hi:[1,0]
	v_max_f32_e32 v77, 0, v77
	v_mul_f32_e32 v86, v76, v76
	v_max_f32_e32 v76, 0, v81
	v_max_f32_e32 v78, 0, v78
	v_mad_i64_i32 v[84:85], s[30:31], v144, s48, v[168:169]
	v_max_f32_e32 v80, 0, v80
	v_mul_f32_e32 v76, v76, v76
	v_mul_f32_e32 v81, v77, v77
	v_max_f32_e32 v77, 0, v82
	v_mul_f32_e32 v82, v78, v78
	v_max_f32_e32 v78, 0, v83
	v_max_f32_e32 v79, 0, v79
	v_pk_mul_f32 v[70:71], v[70:71], v[154:155] op_sel_hi:[1,0]
	v_pk_mul_f32 v[68:69], v[68:69], v[154:155] op_sel_hi:[1,0]
	v_lshl_add_u64 v[84:85], v[84:85], 0, v[150:151]
	v_mul_f32_e32 v80, v80, v80
	v_mul_f32_e32 v77, v77, v77
	v_mul_f32_e32 v78, v78, v78
	v_mul_f32_e32 v79, v79, v79
	v_cvt_pk_bf16_f32 v76, v80, v76
	v_pk_mul_f32 v[74:75], v[74:75], v[154:155] op_sel_hi:[1,0]
	v_pk_mul_f32 v[72:73], v[72:73], v[154:155] op_sel_hi:[1,0]
	v_max_f32_e32 v68, 0, v68
	v_max_f32_e32 v69, 0, v69
	v_max_f32_e32 v70, 0, v70
	v_cvt_pk_bf16_f32 v77, v77, v78
	v_cvt_pk_bf16_f32 v78, v86, v81
	v_cvt_pk_bf16_f32 v79, v82, v79
	global_store_dwordx4 v[84:85], v[76:79], off
	v_max_f32_e32 v72, 0, v72
	v_max_f32_e32 v71, 0, v71
	v_mul_f32_e32 v76, v68, v68
	v_max_f32_e32 v68, 0, v73
	v_mul_f32_e32 v73, v69, v69
	v_max_f32_e32 v69, 0, v74
	v_mul_f32_e32 v74, v70, v70
	v_max_f32_e32 v70, 0, v75
	v_mul_f32_e32 v68, v68, v68
	v_mul_f32_e32 v69, v69, v69
	v_mul_f32_e32 v70, v70, v70
	v_pk_mul_f32 v[60:61], v[60:61], v[152:153] op_sel_hi:[1,0]
	v_mul_f32_e32 v72, v72, v72
	v_mul_f32_e32 v71, v71, v71
	v_cvt_pk_bf16_f32 v68, v72, v68
	v_cvt_pk_bf16_f32 v69, v69, v70
	v_cvt_pk_bf16_f32 v70, v76, v73
	v_pk_mul_f32 v[64:65], v[64:65], v[152:153] op_sel_hi:[1,0]
	v_pk_mul_f32 v[62:63], v[62:63], v[152:153] op_sel_hi:[1,0]
	v_max_f32_e32 v60, 0, v60
	v_cvt_pk_bf16_f32 v71, v74, v71
	global_store_dwordx4 v[84:85], v[68:71], off offset:256
	v_pk_mul_f32 v[66:67], v[66:67], v[152:153] op_sel_hi:[1,0]
	v_max_f32_e32 v61, 0, v61
	v_mul_f32_e32 v70, v60, v60
	v_max_f32_e32 v60, 0, v65
	v_max_f32_e32 v62, 0, v62
	v_mad_i64_i32 v[68:69], s[30:31], v170, s48, v[168:169]
	v_max_f32_e32 v64, 0, v64
	v_mul_f32_e32 v60, v60, v60
	v_mul_f32_e32 v65, v61, v61
	v_max_f32_e32 v61, 0, v66
	v_mul_f32_e32 v66, v62, v62
	v_max_f32_e32 v62, 0, v67
	v_max_f32_e32 v63, 0, v63
	v_pk_mul_f32 v[54:55], v[54:55], v[152:153] op_sel_hi:[1,0]
	v_pk_mul_f32 v[52:53], v[52:53], v[152:153] op_sel_hi:[1,0]
	v_lshl_add_u64 v[68:69], v[68:69], 0, v[150:151]
	v_mul_f32_e32 v64, v64, v64
	v_mul_f32_e32 v61, v61, v61
	v_mul_f32_e32 v62, v62, v62
	v_mul_f32_e32 v63, v63, v63
	v_cvt_pk_bf16_f32 v60, v64, v60
	v_pk_mul_f32 v[58:59], v[58:59], v[152:153] op_sel_hi:[1,0]
	v_pk_mul_f32 v[56:57], v[56:57], v[152:153] op_sel_hi:[1,0]
	v_max_f32_e32 v52, 0, v52
	v_max_f32_e32 v53, 0, v53
	v_max_f32_e32 v54, 0, v54
	v_cvt_pk_bf16_f32 v61, v61, v62
	v_cvt_pk_bf16_f32 v62, v70, v65
	v_cvt_pk_bf16_f32 v63, v66, v63
	global_store_dwordx4 v[68:69], v[60:63], off
	v_max_f32_e32 v56, 0, v56
	v_max_f32_e32 v55, 0, v55
	v_mul_f32_e32 v60, v52, v52
	v_max_f32_e32 v52, 0, v57
	v_mul_f32_e32 v57, v53, v53
	v_max_f32_e32 v53, 0, v58
	v_mul_f32_e32 v58, v54, v54
	v_max_f32_e32 v54, 0, v59
	v_mul_f32_e32 v52, v52, v52
	v_mul_f32_e32 v53, v53, v53
	v_mul_f32_e32 v54, v54, v54
	v_pk_mul_f32 v[44:45], v[44:45], v[162:163] op_sel_hi:[1,0]
	v_mul_f32_e32 v56, v56, v56
	v_mul_f32_e32 v55, v55, v55
	v_cvt_pk_bf16_f32 v52, v56, v52
	v_cvt_pk_bf16_f32 v53, v53, v54
	v_cvt_pk_bf16_f32 v54, v60, v57
	v_pk_mul_f32 v[48:49], v[48:49], v[162:163] op_sel_hi:[1,0]
	v_pk_mul_f32 v[46:47], v[46:47], v[162:163] op_sel_hi:[1,0]
	v_max_f32_e32 v44, 0, v44
	v_cvt_pk_bf16_f32 v55, v58, v55
	global_store_dwordx4 v[68:69], v[52:55], off offset:256
	v_pk_mul_f32 v[50:51], v[50:51], v[162:163] op_sel_hi:[1,0]
	v_max_f32_e32 v45, 0, v45
	v_mul_f32_e32 v54, v44, v44
	v_max_f32_e32 v44, 0, v49
	v_max_f32_e32 v46, 0, v46
	v_mad_i64_i32 v[52:53], s[30:31], v149, s48, v[168:169]
	v_max_f32_e32 v48, 0, v48
	v_mul_f32_e32 v44, v44, v44
	v_mul_f32_e32 v49, v45, v45
	v_max_f32_e32 v45, 0, v50
	v_mul_f32_e32 v50, v46, v46
	v_max_f32_e32 v46, 0, v51
	v_max_f32_e32 v47, 0, v47
	v_pk_mul_f32 v[38:39], v[38:39], v[162:163] op_sel_hi:[1,0]
	v_pk_mul_f32 v[36:37], v[36:37], v[162:163] op_sel_hi:[1,0]
	v_lshl_add_u64 v[52:53], v[52:53], 0, v[150:151]
	v_mul_f32_e32 v48, v48, v48
	v_mul_f32_e32 v45, v45, v45
	v_mul_f32_e32 v46, v46, v46
	v_mul_f32_e32 v47, v47, v47
	v_cvt_pk_bf16_f32 v44, v48, v44
	v_pk_mul_f32 v[42:43], v[42:43], v[162:163] op_sel_hi:[1,0]
	v_pk_mul_f32 v[40:41], v[40:41], v[162:163] op_sel_hi:[1,0]
	v_max_f32_e32 v36, 0, v36
	v_max_f32_e32 v37, 0, v37
	v_max_f32_e32 v38, 0, v38
	v_cvt_pk_bf16_f32 v45, v45, v46
	v_cvt_pk_bf16_f32 v46, v54, v49
	v_cvt_pk_bf16_f32 v47, v50, v47
	global_store_dwordx4 v[52:53], v[44:47], off
	v_max_f32_e32 v40, 0, v40
	v_max_f32_e32 v39, 0, v39
	v_mul_f32_e32 v44, v36, v36
	v_max_f32_e32 v36, 0, v41
	v_mul_f32_e32 v41, v37, v37
	v_max_f32_e32 v37, 0, v42
	v_mul_f32_e32 v42, v38, v38
	v_max_f32_e32 v38, 0, v43
	v_mul_f32_e32 v36, v36, v36
	v_mul_f32_e32 v37, v37, v37
	v_mul_f32_e32 v38, v38, v38
	v_pk_mul_f32 v[28:29], v[28:29], v[166:167] op_sel_hi:[1,0]
	v_mul_f32_e32 v40, v40, v40
	v_mul_f32_e32 v39, v39, v39
	v_cvt_pk_bf16_f32 v36, v40, v36
	v_cvt_pk_bf16_f32 v37, v37, v38
	v_cvt_pk_bf16_f32 v38, v44, v41
	v_pk_mul_f32 v[32:33], v[32:33], v[166:167] op_sel_hi:[1,0]
	v_pk_mul_f32 v[30:31], v[30:31], v[166:167] op_sel_hi:[1,0]
	v_max_f32_e32 v28, 0, v28
	v_cvt_pk_bf16_f32 v39, v42, v39
	global_store_dwordx4 v[52:53], v[36:39], off offset:256
	v_pk_mul_f32 v[34:35], v[34:35], v[166:167] op_sel_hi:[1,0]
	v_max_f32_e32 v29, 0, v29
	v_mul_f32_e32 v38, v28, v28
	v_max_f32_e32 v28, 0, v33
	v_max_f32_e32 v30, 0, v30
	v_mad_i64_i32 v[36:37], s[30:31], v147, s48, v[168:169]
	v_max_f32_e32 v32, 0, v32
	v_mul_f32_e32 v28, v28, v28
	v_mul_f32_e32 v33, v29, v29
	v_max_f32_e32 v29, 0, v34
	v_mul_f32_e32 v34, v30, v30
	v_max_f32_e32 v30, 0, v35
	v_max_f32_e32 v31, 0, v31
	v_pk_mul_f32 v[22:23], v[22:23], v[166:167] op_sel_hi:[1,0]
	v_pk_mul_f32 v[20:21], v[20:21], v[166:167] op_sel_hi:[1,0]
	v_lshl_add_u64 v[36:37], v[36:37], 0, v[150:151]
	v_mul_f32_e32 v32, v32, v32
	v_mul_f32_e32 v29, v29, v29
	v_mul_f32_e32 v30, v30, v30
	v_mul_f32_e32 v31, v31, v31
	v_cvt_pk_bf16_f32 v28, v32, v28
	v_pk_mul_f32 v[26:27], v[26:27], v[166:167] op_sel_hi:[1,0]
	v_pk_mul_f32 v[24:25], v[24:25], v[166:167] op_sel_hi:[1,0]
	v_max_f32_e32 v20, 0, v20
	v_max_f32_e32 v21, 0, v21
	v_max_f32_e32 v22, 0, v22
	v_cvt_pk_bf16_f32 v29, v29, v30
	v_cvt_pk_bf16_f32 v30, v38, v33
	v_cvt_pk_bf16_f32 v31, v34, v31
	global_store_dwordx4 v[36:37], v[28:31], off
	v_max_f32_e32 v24, 0, v24
	v_max_f32_e32 v23, 0, v23
	v_mul_f32_e32 v28, v20, v20
	v_max_f32_e32 v20, 0, v25
	v_mul_f32_e32 v25, v21, v21
	v_max_f32_e32 v21, 0, v26
	v_mul_f32_e32 v26, v22, v22
	v_max_f32_e32 v22, 0, v27
	v_mul_f32_e32 v20, v20, v20
	v_mul_f32_e32 v21, v21, v21
	v_mul_f32_e32 v22, v22, v22
	v_pk_mul_f32 v[12:13], v[12:13], v[164:165] op_sel_hi:[1,0]
	v_mul_f32_e32 v24, v24, v24
	v_mul_f32_e32 v23, v23, v23
	v_cvt_pk_bf16_f32 v20, v24, v20
	v_cvt_pk_bf16_f32 v21, v21, v22
	v_cvt_pk_bf16_f32 v22, v28, v25
	v_pk_mul_f32 v[16:17], v[16:17], v[164:165] op_sel_hi:[1,0]
	v_pk_mul_f32 v[14:15], v[14:15], v[164:165] op_sel_hi:[1,0]
	v_max_f32_e32 v12, 0, v12
	v_cvt_pk_bf16_f32 v23, v26, v23
	global_store_dwordx4 v[36:37], v[20:23], off offset:256
	v_pk_mul_f32 v[18:19], v[18:19], v[164:165] op_sel_hi:[1,0]
	v_max_f32_e32 v13, 0, v13
	v_mul_f32_e32 v22, v12, v12
	v_max_f32_e32 v12, 0, v17
	v_max_f32_e32 v14, 0, v14
	v_mad_i64_i32 v[20:21], s[30:31], v145, s48, v[168:169]
	v_max_f32_e32 v16, 0, v16
	v_mul_f32_e32 v12, v12, v12
	v_mul_f32_e32 v17, v13, v13
	v_max_f32_e32 v13, 0, v18
	v_mul_f32_e32 v18, v14, v14
	v_max_f32_e32 v14, 0, v19
	v_max_f32_e32 v15, 0, v15
	v_pk_mul_f32 v[6:7], v[6:7], v[164:165] op_sel_hi:[1,0]
	v_pk_mul_f32 v[4:5], v[4:5], v[164:165] op_sel_hi:[1,0]
	v_lshl_add_u64 v[20:21], v[20:21], 0, v[150:151]
	v_mul_f32_e32 v16, v16, v16
	v_mul_f32_e32 v13, v13, v13
	v_mul_f32_e32 v14, v14, v14
	v_mul_f32_e32 v15, v15, v15
	v_cvt_pk_bf16_f32 v12, v16, v12
	v_pk_mul_f32 v[10:11], v[10:11], v[164:165] op_sel_hi:[1,0]
	v_pk_mul_f32 v[8:9], v[8:9], v[164:165] op_sel_hi:[1,0]
	v_max_f32_e32 v4, 0, v4
	v_max_f32_e32 v5, 0, v5
	v_max_f32_e32 v6, 0, v6
	v_cvt_pk_bf16_f32 v13, v13, v14
	v_cvt_pk_bf16_f32 v14, v22, v17
	v_cvt_pk_bf16_f32 v15, v18, v15
	global_store_dwordx4 v[20:21], v[12:15], off
	v_max_f32_e32 v7, 0, v7
	v_max_f32_e32 v8, 0, v8
	v_mul_f32_e32 v12, v4, v4
	v_max_f32_e32 v4, 0, v9
	v_mul_f32_e32 v9, v5, v5
	v_max_f32_e32 v5, 0, v10
	v_mul_f32_e32 v10, v6, v6
	v_max_f32_e32 v6, 0, v11
	v_mul_f32_e32 v4, v4, v4
	v_mul_f32_e32 v5, v5, v5
	v_mul_f32_e32 v6, v6, v6
	v_mul_f32_e32 v7, v7, v7
	s_mov_b64 s[30:31], -1
	v_mul_f32_e32 v8, v8, v8
	v_cvt_pk_bf16_f32 v4, v8, v4
	v_cvt_pk_bf16_f32 v5, v5, v6
	v_cvt_pk_bf16_f32 v6, v12, v9
	v_cvt_pk_bf16_f32 v7, v10, v7
	global_store_dwordx4 v[20:21], v[4:7], off offset:256
	s_cbranch_vccnz .LBB0_1159
	s_andn2_b64 vcc, exec, s[10:11]
	s_cbranch_vccnz .LBB0_1158
	s_barrier
	s_branch .LBB0_1158
